# GEMM K-loops: s_nop wait-state fillers replaced by reordered useful instructions (counted waits shifted in front of the second DMA)
# speedup vs baseline: 1.0080x; 1.0080x over previous
; #define PG8_STAGE(bufoff, gbase, voff) do { _Pragma("unroll") for (int _i = 0; _i < 2; ++_i) \
;         __builtin_amdgcn_global_load_lds((const unsigned*)((const char*)(gbase) + (voff)[_i]), (LAS unsigned*)(lds + (bufoff) + ldsw + _i * 8192), 16, 0, 0); } while (0)
; #define PG8_LDA(dst, b, h) do { _Pragma("unroll") for (int m = 0; m < 4; ++m) _Pragma("unroll") for (int k = 0; k < 2; ++k) dst[m][k] = *(const LAS bf16x8*)(lds + PG8_SA(b, h) + aoff + m * 2048 + k * 1024); } while (0)
; #define PG8_LDB(dst, b, h) do { _Pragma("unroll") for (int n = 0; n < 2; ++n) _Pragma("unroll") for (int k = 0; k < 2; ++k) dst[n][k] = *(const LAS bf16x8*)(lds + PG8_SB(b, h) + boff + n * 2048 + k * 1024); } while (0)
; #define PG8_MMA(ai, bj, At, Bt) do { __builtin_amdgcn_s_setprio(1); _Pragma("unroll") for (int m = 0; m < 4; ++m) _Pragma("unroll") for (int n = 0; n < 2; ++n) _Pragma("unroll") for (int k = 0; k < 2; ++k) \
;         acc[ai][bj][m][n] = __builtin_amdgcn_mfma_f32_16x16x32_bf16(Bt[n][k], At[m][k], acc[ai][bj][m][n], 0, 0, 0); __builtin_amdgcn_s_setprio(0); } while (0)
; #define PG8_WAIT_V(n) asm volatile("s_waitcnt vmcnt(" #n ")" ::: "memory")
; template <class Epi>
; __device__ __forceinline__ void gemm_phase(LAS unsigned char* lds, const Gemm g, const StaticOrder& S, const Epi& E) {
;     ...
;         for (int t = 0; t < nt; t += 2) {
;             const bool last = (t == nt - 2);
;             const char* a1 = cA + (size_t)(t + 1) * kstep;
;             const char* a2 = last ? nA : cA + (size_t)(t + 2) * kstep; const char* b2 = last ? nB : cB + (size_t)(t + 2) * kstep;
;             const char* a3 = a2 + kstep; const char* b3 = b2 + kstep;
;             PG8_LDB(B0, 0, 0); PG8_SCHED; PG8_LDA(At, 0, 0); PG8_STAGE(PG8_SA(1, 1), a1 + hstep, voffA);
;             PG8_WAIT_L(8); PG8_BAR; PG8_WAIT_L(0); PG8_MMA(0, 0, At, B0); PG8_BAR; PG8_SCHED;
;             PG8_LDB(B1, 0, 1); PG8_STAGE(PG8_SB(0, 0), b2, voffB);
;             PG8_BAR; PG8_WAIT_L(0); PG8_MMA(0, 1, At, B1); PG8_BAR;
;             PG8_LDA(At, 0, 1); PG8_STAGE(PG8_SA(0, 0), a2, voffA);
;             PG8_BAR; PG8_WAIT_L(0); PG8_MMA(1, 0, At, B0); PG8_BAR; PG8_SCHED;
;             PG8_STAGE(PG8_SB(0, 1), b2 + hstep, voffB);
;             PG8_WAIT_V(6); PG8_BAR; PG8_MMA(1, 1, At, B1); PG8_BAR;
;             PG8_LDB(B0, 1, 0); PG8_SCHED; PG8_LDA(At, 1, 0); PG8_STAGE(PG8_SA(0, 1), a2 + hstep, voffA);
.LBB0_64:
	s_add_u32 s58, s56, 0xfff80080
	s_addc_u32 s59, s57, -1
	s_add_i32 s86, 0, 0x10000
	s_cmp_eq_u32 s85, 28
	s_cselect_b32 s61, s49, s59
	s_cselect_b32 s60, s81, s58
	s_cselect_b32 s59, s47, s84
	s_cselect_b32 s58, s82, s83
	s_add_i32 m0, s55, 0xc000
	ds_read_b128 v[170:173], v151
	ds_read_b128 v[174:177], v151 offset:1024
	ds_read_b128 v[178:181], v151 offset:2048
	ds_read_b128 v[182:185], v151 offset:3072
	ds_read_b128 v[186:189], v151 offset:4096
	ds_read_b128 v[190:193], v151 offset:5120
	ds_read_b128 v[194:197], v151 offset:6144
	ds_read_b128 v[198:201], v151 offset:7168
	global_load_lds_dwordx4 v136, s[56:57]
	s_add_i32 m0, s55, 0xe000
	s_waitcnt lgkmcnt(8)
	global_load_lds_dwordx4 v138, s[56:57]
	s_barrier
	s_waitcnt lgkmcnt(0)
	v_mfma_f32_16x16x32_bf16 v[126:129], v[154:157], v[170:173], v[126:129]
	v_mfma_f32_16x16x32_bf16 v[122:125], v[162:165], v[170:173], v[122:125]
	v_mfma_f32_16x16x32_bf16 v[110:113], v[154:157], v[178:181], v[110:113]
	v_mfma_f32_16x16x32_bf16 v[106:109], v[162:165], v[178:181], v[106:109]
	v_mfma_f32_16x16x32_bf16 v[94:97], v[154:157], v[186:189], v[94:97]
	v_mfma_f32_16x16x32_bf16 v[90:93], v[162:165], v[186:189], v[90:93]
	v_mfma_f32_16x16x32_bf16 v[78:81], v[154:157], v[194:197], v[78:81]
	v_mfma_f32_16x16x32_bf16 v[74:77], v[162:165], v[194:197], v[74:77]
	v_mfma_f32_16x16x32_bf16 v[126:129], v[158:161], v[174:177], v[126:129]
	v_mfma_f32_16x16x32_bf16 v[122:125], v[166:169], v[174:177], v[122:125]
	v_mfma_f32_16x16x32_bf16 v[110:113], v[158:161], v[182:185], v[110:113]
	v_mfma_f32_16x16x32_bf16 v[106:109], v[166:169], v[182:185], v[106:109]
	v_mfma_f32_16x16x32_bf16 v[94:97], v[158:161], v[190:193], v[94:97]
	v_mfma_f32_16x16x32_bf16 v[90:93], v[166:169], v[190:193], v[90:93]
	v_mfma_f32_16x16x32_bf16 v[78:81], v[158:161], v[198:201], v[78:81]
	v_mfma_f32_16x16x32_bf16 v[74:77], v[166:169], v[198:201], v[74:77]
	s_barrier
	s_add_i32 s86, s86, s69
	s_add_u32 s98, s58, s22
	s_addc_u32 s99, s59, s23
	s_mov_b32 m0, s86
	ds_read_b128 v[208:211], v202 offset:16384
	ds_read_b128 v[212:215], v202 offset:17408
	ds_read_b128 v[216:219], v202 offset:18432
	ds_read_b128 v[220:223], v202 offset:19456
	global_load_lds_dwordx4 v0, s[58:59]
	s_add_i32 m0, s86, 0x2000
	s_add_i32 s88, 0, 0x14000
	global_load_lds_dwordx4 v130, s[58:59]
	s_barrier
	s_waitcnt lgkmcnt(0)
	v_mfma_f32_16x16x32_bf16 v[118:121], v[208:211], v[170:173], v[118:121]
	v_mfma_f32_16x16x32_bf16 v[114:117], v[216:219], v[170:173], v[114:117]
	v_mfma_f32_16x16x32_bf16 v[102:105], v[208:211], v[178:181], v[102:105]
	v_mfma_f32_16x16x32_bf16 v[98:101], v[216:219], v[178:181], v[98:101]
	v_mfma_f32_16x16x32_bf16 v[86:89], v[208:211], v[186:189], v[86:89]
	v_mfma_f32_16x16x32_bf16 v[82:85], v[216:219], v[186:189], v[82:85]
	v_mfma_f32_16x16x32_bf16 v[70:73], v[208:211], v[194:197], v[70:73]
	v_mfma_f32_16x16x32_bf16 v[66:69], v[216:219], v[194:197], v[66:69]
	v_mfma_f32_16x16x32_bf16 v[118:121], v[212:215], v[174:177], v[118:121]
	v_mfma_f32_16x16x32_bf16 v[114:117], v[220:223], v[174:177], v[114:117]
	v_mfma_f32_16x16x32_bf16 v[102:105], v[212:215], v[182:185], v[102:105]
	v_mfma_f32_16x16x32_bf16 v[98:101], v[220:223], v[182:185], v[98:101]
	v_mfma_f32_16x16x32_bf16 v[86:89], v[212:215], v[190:193], v[86:89]
	v_mfma_f32_16x16x32_bf16 v[82:85], v[220:223], v[190:193], v[82:85]
	v_mfma_f32_16x16x32_bf16 v[70:73], v[212:215], v[198:201], v[70:73]
	v_mfma_f32_16x16x32_bf16 v[66:69], v[220:223], v[198:201], v[66:69]
	s_barrier
	ds_read_b128 v[170:173], v151 offset:16384
	ds_read_b128 v[174:177], v151 offset:17408
	ds_read_b128 v[178:181], v151 offset:18432
	ds_read_b128 v[182:185], v151 offset:19456
	ds_read_b128 v[186:189], v151 offset:20480
	ds_read_b128 v[190:193], v151 offset:21504
	ds_read_b128 v[194:197], v151 offset:22528
	s_mov_b32 m0, s55
	s_add_u32 s100, s60, s22
	s_addc_u32 s101, s61, s23
	ds_read_b128 v[198:201], v151 offset:23552
	global_load_lds_dwordx4 v134, s[60:61]
	s_mov_b32 m0, s72
	s_waitcnt vmcnt(9)
	global_load_lds_dwordx4 v132, s[60:61]
	s_barrier
	s_waitcnt lgkmcnt(0)
	v_mfma_f32_16x16x32_bf16 v[62:65], v[154:157], v[170:173], v[62:65]
	v_mfma_f32_16x16x32_bf16 v[58:61], v[162:165], v[170:173], v[58:61]
	v_mfma_f32_16x16x32_bf16 v[54:57], v[154:157], v[178:181], v[54:57]
	v_mfma_f32_16x16x32_bf16 v[46:49], v[162:165], v[178:181], v[46:49]
	v_mfma_f32_16x16x32_bf16 v[38:41], v[154:157], v[186:189], v[38:41]
	v_mfma_f32_16x16x32_bf16 v[30:33], v[162:165], v[186:189], v[30:33]
	v_mfma_f32_16x16x32_bf16 v[22:25], v[154:157], v[194:197], v[22:25]
	v_mfma_f32_16x16x32_bf16 v[14:17], v[162:165], v[194:197], v[14:17]
	v_mfma_f32_16x16x32_bf16 v[62:65], v[158:161], v[174:177], v[62:65]
	v_mfma_f32_16x16x32_bf16 v[58:61], v[166:169], v[174:177], v[58:61]
	v_mfma_f32_16x16x32_bf16 v[54:57], v[158:161], v[182:185], v[54:57]
	v_mfma_f32_16x16x32_bf16 v[46:49], v[166:169], v[182:185], v[46:49]
	v_mfma_f32_16x16x32_bf16 v[38:41], v[158:161], v[190:193], v[38:41]
	v_mfma_f32_16x16x32_bf16 v[30:33], v[166:169], v[190:193], v[30:33]
	v_mfma_f32_16x16x32_bf16 v[22:25], v[158:161], v[198:201], v[22:25]
	v_mfma_f32_16x16x32_bf16 v[14:17], v[166:169], v[198:201], v[14:17]
	s_barrier
	ds_read_b128 v[154:157], v202 offset:32768
	ds_read_b128 v[158:161], v202 offset:33792
	ds_read_b128 v[162:165], v202 offset:34816
	ds_read_b128 v[166:169], v202 offset:35840
	s_add_i32 s88, s88, s69
	s_mov_b32 m0, s88
	s_add_u32 s86, s58, 0x80000
	s_addc_u32 s87, s59, 0
	global_load_lds_dwordx4 v0, s[86:87]
	s_add_i32 m0, s88, 0x2000
	s_waitcnt vmcnt(5)
	global_load_lds_dwordx4 v130, s[86:87]
	s_barrier
; #define PG8_STAGE(bufoff, gbase, voff) do { _Pragma("unroll") for (int _i = 0; _i < 2; ++_i) \
;         __builtin_amdgcn_global_load_lds((const unsigned*)((const char*)(gbase) + (voff)[_i]), (LAS unsigned*)(lds + (bufoff) + ldsw + _i * 8192), 16, 0, 0); } while (0)
; #define PG8_LDA(dst, b, h) do { _Pragma("unroll") for (int m = 0; m < 4; ++m) _Pragma("unroll") for (int k = 0; k < 2; ++k) dst[m][k] = *(const LAS bf16x8*)(lds + PG8_SA(b, h) + aoff + m * 2048 + k * 1024); } while (0)
; #define PG8_LDB(dst, b, h) do { _Pragma("unroll") for (int n = 0; n < 2; ++n) _Pragma("unroll") for (int k = 0; k < 2; ++k) dst[n][k] = *(const LAS bf16x8*)(lds + PG8_SB(b, h) + boff + n * 2048 + k * 1024); } while (0)
; #define PG8_MMA(ai, bj, At, Bt) do { __builtin_amdgcn_s_setprio(1); _Pragma("unroll") for (int m = 0; m < 4; ++m) _Pragma("unroll") for (int n = 0; n < 2; ++n) _Pragma("unroll") for (int k = 0; k < 2; ++k) \
;         acc[ai][bj][m][n] = __builtin_amdgcn_mfma_f32_16x16x32_bf16(Bt[n][k], At[m][k], acc[ai][bj][m][n], 0, 0, 0); __builtin_amdgcn_s_setprio(0); } while (0)
; #define PG8_WAIT_V(n) asm volatile("s_waitcnt vmcnt(" #n ")" ::: "memory")
; #define PG8_WAIT_L(n) asm volatile("s_waitcnt lgkmcnt(" #n ")" ::: "memory")
; #define PG8_BAR __builtin_amdgcn_s_barrier()
; #define PG8_SCHED __builtin_amdgcn_sched_barrier(0)
; template <class Epi>
; __device__ __forceinline__ void gemm_phase(LAS unsigned char* lds, const Gemm g, const StaticOrder& S, const Epi& E) {
;     ...
;             PG8_LDB(B0, 1, 0); PG8_SCHED; PG8_LDA(At, 1, 0); PG8_STAGE(PG8_SA(0, 1), a2 + hstep, voffA);
;             PG8_WAIT_L(8); PG8_BAR; PG8_WAIT_L(0); PG8_MMA(0, 0, At, B0); PG8_BAR; PG8_SCHED;
;             PG8_LDB(B1, 1, 1); PG8_STAGE(PG8_SB(1, 0), b3, voffB);
;             PG8_BAR; PG8_WAIT_L(0); PG8_MMA(0, 1, At, B1); PG8_BAR;
;             PG8_LDA(At, 1, 1); PG8_STAGE(PG8_SA(1, 0), a3, voffA);
;             PG8_BAR; PG8_WAIT_L(0); PG8_MMA(1, 0, At, B0); PG8_BAR; PG8_SCHED;
;             PG8_STAGE(PG8_SB(1, 1), b3 + hstep, voffB);
;             PG8_WAIT_V(6); PG8_BAR; PG8_MMA(1, 1, At, B1); PG8_BAR;
	v_mfma_f32_16x16x32_bf16 v[50:53], v[208:211], v[170:173], v[50:53]
	v_mfma_f32_16x16x32_bf16 v[42:45], v[216:219], v[170:173], v[42:45]
	v_mfma_f32_16x16x32_bf16 v[34:37], v[208:211], v[178:181], v[34:37]
	v_mfma_f32_16x16x32_bf16 v[26:29], v[216:219], v[178:181], v[26:29]
	v_mfma_f32_16x16x32_bf16 v[18:21], v[208:211], v[186:189], v[18:21]
	v_mfma_f32_16x16x32_bf16 v[10:13], v[216:219], v[186:189], v[10:13]
	v_mfma_f32_16x16x32_bf16 v[6:9], v[208:211], v[194:197], v[6:9]
	v_mfma_f32_16x16x32_bf16 v[2:5], v[216:219], v[194:197], v[2:5]
	v_mfma_f32_16x16x32_bf16 v[50:53], v[212:215], v[174:177], v[50:53]
	v_mfma_f32_16x16x32_bf16 v[42:45], v[220:223], v[174:177], v[42:45]
	v_mfma_f32_16x16x32_bf16 v[34:37], v[212:215], v[182:185], v[34:37]
	v_mfma_f32_16x16x32_bf16 v[26:29], v[220:223], v[182:185], v[26:29]
	v_mfma_f32_16x16x32_bf16 v[18:21], v[212:215], v[190:193], v[18:21]
	v_mfma_f32_16x16x32_bf16 v[10:13], v[220:223], v[190:193], v[10:13]
	v_mfma_f32_16x16x32_bf16 v[6:9], v[212:215], v[198:201], v[6:9]
	v_mfma_f32_16x16x32_bf16 v[2:5], v[220:223], v[198:201], v[2:5]
	s_barrier
	s_add_u32 s60, s60, 0x80000
	s_addc_u32 s61, s61, 0
	s_mov_b32 m0, s73
	ds_read_b128 v[170:173], v151 offset:32768
	ds_read_b128 v[174:177], v151 offset:33792
	ds_read_b128 v[178:181], v151 offset:34816
	ds_read_b128 v[182:185], v151 offset:35840
	ds_read_b128 v[186:189], v151 offset:36864
	ds_read_b128 v[190:193], v151 offset:37888
	ds_read_b128 v[194:197], v151 offset:38912
	s_add_i32 s86, 0, 0x18000
	ds_read_b128 v[198:201], v151 offset:39936
	global_load_lds_dwordx4 v134, s[60:61]
	s_mov_b32 m0, s74
	s_waitcnt lgkmcnt(8)
	global_load_lds_dwordx4 v132, s[60:61]
	s_barrier
	s_waitcnt lgkmcnt(0)
	v_mfma_f32_16x16x32_bf16 v[126:129], v[154:157], v[170:173], v[126:129]
	v_mfma_f32_16x16x32_bf16 v[122:125], v[162:165], v[170:173], v[122:125]
	v_mfma_f32_16x16x32_bf16 v[110:113], v[154:157], v[178:181], v[110:113]
	v_mfma_f32_16x16x32_bf16 v[106:109], v[162:165], v[178:181], v[106:109]
	v_mfma_f32_16x16x32_bf16 v[94:97], v[154:157], v[186:189], v[94:97]
	v_mfma_f32_16x16x32_bf16 v[90:93], v[162:165], v[186:189], v[90:93]
	v_mfma_f32_16x16x32_bf16 v[78:81], v[154:157], v[194:197], v[78:81]
	v_mfma_f32_16x16x32_bf16 v[74:77], v[162:165], v[194:197], v[74:77]
	v_mfma_f32_16x16x32_bf16 v[126:129], v[158:161], v[174:177], v[126:129]
	v_mfma_f32_16x16x32_bf16 v[122:125], v[166:169], v[174:177], v[122:125]
	v_mfma_f32_16x16x32_bf16 v[110:113], v[158:161], v[182:185], v[110:113]
	v_mfma_f32_16x16x32_bf16 v[106:109], v[166:169], v[182:185], v[106:109]
	v_mfma_f32_16x16x32_bf16 v[94:97], v[158:161], v[190:193], v[94:97]
	v_mfma_f32_16x16x32_bf16 v[90:93], v[166:169], v[190:193], v[90:93]
	v_mfma_f32_16x16x32_bf16 v[78:81], v[158:161], v[198:201], v[78:81]
	v_mfma_f32_16x16x32_bf16 v[74:77], v[166:169], v[198:201], v[74:77]
	s_barrier
	s_add_i32 s61, s86, s69
	s_mov_b32 m0, s61
	ds_read_b128 v[208:211], v202 offset:49152
	ds_read_b128 v[212:215], v202 offset:50176
	ds_read_b128 v[216:219], v202 offset:51200
	ds_read_b128 v[220:223], v202 offset:52224
	global_load_lds_dwordx4 v0, s[98:99]
	s_add_i32 m0, s61, 0x2000
	s_add_i32 s60, 0, 0x1c000
	global_load_lds_dwordx4 v130, s[98:99]
	s_barrier
	s_waitcnt lgkmcnt(0)
	v_mfma_f32_16x16x32_bf16 v[118:121], v[208:211], v[170:173], v[118:121]
	v_mfma_f32_16x16x32_bf16 v[114:117], v[216:219], v[170:173], v[114:117]
	v_mfma_f32_16x16x32_bf16 v[102:105], v[208:211], v[178:181], v[102:105]
	v_mfma_f32_16x16x32_bf16 v[98:101], v[216:219], v[178:181], v[98:101]
	v_mfma_f32_16x16x32_bf16 v[86:89], v[208:211], v[186:189], v[86:89]
	v_mfma_f32_16x16x32_bf16 v[82:85], v[216:219], v[186:189], v[82:85]
	v_mfma_f32_16x16x32_bf16 v[70:73], v[208:211], v[194:197], v[70:73]
	v_mfma_f32_16x16x32_bf16 v[66:69], v[216:219], v[194:197], v[66:69]
	v_mfma_f32_16x16x32_bf16 v[118:121], v[212:215], v[174:177], v[118:121]
	v_mfma_f32_16x16x32_bf16 v[114:117], v[220:223], v[174:177], v[114:117]
	v_mfma_f32_16x16x32_bf16 v[102:105], v[212:215], v[182:185], v[102:105]
	v_mfma_f32_16x16x32_bf16 v[98:101], v[220:223], v[182:185], v[98:101]
	v_mfma_f32_16x16x32_bf16 v[86:89], v[212:215], v[190:193], v[86:89]
	v_mfma_f32_16x16x32_bf16 v[82:85], v[220:223], v[190:193], v[82:85]
	v_mfma_f32_16x16x32_bf16 v[70:73], v[212:215], v[198:201], v[70:73]
	v_mfma_f32_16x16x32_bf16 v[66:69], v[220:223], v[198:201], v[66:69]
	s_barrier
	ds_read_b128 v[170:173], v151 offset:49152
	ds_read_b128 v[174:177], v151 offset:50176
	ds_read_b128 v[178:181], v151 offset:51200
	ds_read_b128 v[182:185], v151 offset:52224
	ds_read_b128 v[186:189], v151 offset:53248
	ds_read_b128 v[190:193], v151 offset:54272
	ds_read_b128 v[194:197], v151 offset:55296
	s_mov_b32 m0, s76
	ds_read_b128 v[198:201], v151 offset:56320
	global_load_lds_dwordx4 v134, s[100:101]
	s_mov_b32 m0, s77
	s_waitcnt vmcnt(9)
	global_load_lds_dwordx4 v132, s[100:101]
	s_barrier
	s_waitcnt lgkmcnt(0)
	v_mfma_f32_16x16x32_bf16 v[62:65], v[154:157], v[170:173], v[62:65]
	v_mfma_f32_16x16x32_bf16 v[58:61], v[162:165], v[170:173], v[58:61]
	v_mfma_f32_16x16x32_bf16 v[54:57], v[154:157], v[178:181], v[54:57]
	v_mfma_f32_16x16x32_bf16 v[46:49], v[162:165], v[178:181], v[46:49]
	v_mfma_f32_16x16x32_bf16 v[38:41], v[154:157], v[186:189], v[38:41]
	v_mfma_f32_16x16x32_bf16 v[30:33], v[162:165], v[186:189], v[30:33]
	v_mfma_f32_16x16x32_bf16 v[22:25], v[154:157], v[194:197], v[22:25]
	v_mfma_f32_16x16x32_bf16 v[14:17], v[162:165], v[194:197], v[14:17]
	v_mfma_f32_16x16x32_bf16 v[62:65], v[158:161], v[174:177], v[62:65]
	v_mfma_f32_16x16x32_bf16 v[58:61], v[166:169], v[174:177], v[58:61]
	v_mfma_f32_16x16x32_bf16 v[54:57], v[158:161], v[182:185], v[54:57]
	v_mfma_f32_16x16x32_bf16 v[46:49], v[166:169], v[182:185], v[46:49]
	v_mfma_f32_16x16x32_bf16 v[38:41], v[158:161], v[190:193], v[38:41]
	v_mfma_f32_16x16x32_bf16 v[30:33], v[166:169], v[190:193], v[30:33]
	v_mfma_f32_16x16x32_bf16 v[22:25], v[158:161], v[198:201], v[22:25]
	v_mfma_f32_16x16x32_bf16 v[14:17], v[166:169], v[198:201], v[14:17]
	s_barrier
; __device__ __forceinline__ unsigned pk2(float lo, float hi) { f32x2 v = {lo, hi}; bf16x2_t b = __builtin_convertvector(v, bf16x2_t); return __builtin_bit_cast(unsigned, b); }
; #define PG8_MMA(ai, bj, At, Bt) do { __builtin_amdgcn_s_setprio(1); _Pragma("unroll") for (int m = 0; m < 4; ++m) _Pragma("unroll") for (int n = 0; n < 2; ++n) _Pragma("unroll") for (int k = 0; k < 2; ++k) \
;         acc[ai][bj][m][n] = __builtin_amdgcn_mfma_f32_16x16x32_bf16(Bt[n][k], At[m][k], acc[ai][bj][m][n], 0, 0, 0); __builtin_amdgcn_s_setprio(0); } while (0)
; #define PG8_WAIT_V(n) asm volatile("s_waitcnt vmcnt(" #n ")" ::: "memory")
; #define PG8_BAR __builtin_amdgcn_s_barrier()
;     __device__ __forceinline__ void operator()(const AccT& acc, const Unit& u, int wr, int wc, int fr, int fq) const {
;         const int row0 = u.pm * BM + wr * 64 + fr, col0 = u.pn * BM + wc * 32 + 8 * fq;
;         float rsv[8];
;         if (ss) {
;             const int ln = (fq << 4) | fr;
;             float sa = ss[u.pm * BM + wr * 64 + ln], sb = ss[u.pm * BM + HALF + wr * 64 + ln];
;             sa = __builtin_amdgcn_rsqf(sa * (1.0f / DM) + EPS); sb = __builtin_amdgcn_rsqf(sb * (1.0f / DM) + EPS);
; #pragma unroll
;             for (int m = 0; m < 4; ++m) { rsv[m] = __shfl(sa, 16 * m + fr); rsv[4 + m] = __shfl(sb, 16 * m + fr); }
;         } else {
; #pragma unroll
;             for (int i = 0; i < 8; ++i) rsv[i] = 1.0f;
;         }
; #pragma unroll
;         for (int ai = 0; ai < 2; ++ai)
; #pragma unroll
;             for (int m = 0; m < 4; ++m) {
;                 const int row = row0 + ai * HALF + m * 16;
;                 const float rs = rsv[ai * 4 + m];
; #pragma unroll
;                 for (int bj = 0; bj < 2; ++bj) {
;                     const f32x4 v0 = acc[ai][bj][m][0] * rs, v1 = acc[ai][bj][m][1] * rs;
;                     u32x4 w; w.x = pk2(v0[0], v0[1]); w.y = pk2(v0[2], v0[3]); w.z = pk2(v1[0], v1[1]); w.w = pk2(v1[2], v1[3]);
;                     *(u32x4*)(out + (size_t)row * ldo + col0 + bj * HALF) = w;
;                 }
; template <class Epi>
; __device__ __forceinline__ void gemm_phase(LAS unsigned char* lds, const Gemm g, const StaticOrder& S, const Epi& E) {
;     ...
;             PG8_WAIT_V(6); PG8_BAR; PG8_MMA(1, 1, At, B1); PG8_BAR;
;         }
;         E(acc, cur, wr, wc, fr, fq);
	ds_read_b128 v[154:157], v202
	ds_read_b128 v[158:161], v202 offset:1024
	ds_read_b128 v[162:165], v202 offset:2048
	s_add_i32 s85, s85, 2
	s_add_u32 s56, s56, 0x100
	s_addc_u32 s57, s57, 0
	s_add_u32 s83, s83, 0x100
	s_addc_u32 s84, s84, 0
	ds_read_b128 v[166:169], v202 offset:3072
	s_add_i32 s60, s60, s69
	s_mov_b32 m0, s60
	s_add_u32 s58, s58, 0x80080
	s_addc_u32 s59, s59, 0
	global_load_lds_dwordx4 v0, s[58:59]
	s_add_i32 m0, s60, 0x2000
	s_waitcnt vmcnt(5)
	global_load_lds_dwordx4 v130, s[58:59]
	s_barrier
	v_mfma_f32_16x16x32_bf16 v[50:53], v[208:211], v[170:173], v[50:53]
	v_mfma_f32_16x16x32_bf16 v[42:45], v[216:219], v[170:173], v[42:45]
	v_mfma_f32_16x16x32_bf16 v[34:37], v[208:211], v[178:181], v[34:37]
	v_mfma_f32_16x16x32_bf16 v[26:29], v[216:219], v[178:181], v[26:29]
	v_mfma_f32_16x16x32_bf16 v[18:21], v[208:211], v[186:189], v[18:21]
	v_mfma_f32_16x16x32_bf16 v[10:13], v[216:219], v[186:189], v[10:13]
	v_mfma_f32_16x16x32_bf16 v[6:9], v[208:211], v[194:197], v[6:9]
	v_mfma_f32_16x16x32_bf16 v[2:5], v[216:219], v[194:197], v[2:5]
	v_mfma_f32_16x16x32_bf16 v[50:53], v[212:215], v[174:177], v[50:53]
	v_mfma_f32_16x16x32_bf16 v[42:45], v[220:223], v[174:177], v[42:45]
	v_mfma_f32_16x16x32_bf16 v[34:37], v[212:215], v[182:185], v[34:37]
	v_mfma_f32_16x16x32_bf16 v[26:29], v[220:223], v[182:185], v[26:29]
	v_mfma_f32_16x16x32_bf16 v[18:21], v[212:215], v[190:193], v[18:21]
	v_mfma_f32_16x16x32_bf16 v[10:13], v[220:223], v[190:193], v[10:13]
	v_mfma_f32_16x16x32_bf16 v[6:9], v[212:215], v[198:201], v[6:9]
	v_mfma_f32_16x16x32_bf16 v[2:5], v[220:223], v[198:201], v[2:5]
	s_cmp_gt_u32 s85, 29
	s_barrier
	s_cbranch_scc0 .LBB0_64
	s_waitcnt lgkmcnt(0)
	s_lshl_b32 s47, s54, 8
	s_add_i32 s47, s47, s75
	v_or_b32_e32 v154, s47, v145
	v_ashrrev_i32_e32 v155, 31, v154
	v_lshl_add_u64 v[154:155], v[154:155], 2, s[2:3]
	global_load_dword v140, v[154:155], off
	v_add_u32_e32 v154, s47, v147
	v_ashrrev_i32_e32 v155, 31, v154
	v_lshl_add_u64 v[154:155], v[154:155], 2, s[2:3]
	global_load_dword v142, v[154:155], off
	v_lshl_or_b32 v158, s80, 8, v149
	v_ashrrev_i32_e32 v159, 31, v158
	s_and_b64 vcc, exec, s[36:37]
	s_mov_b32 s80, s46
	s_mov_b32 s54, s48
	s_mov_b64 s[58:59], s[52:53]
	s_waitcnt vmcnt(0)
	v_fmamk_f32 v140, v140, 0x3a000000, v233
	v_rsq_f32_e32 v140, v140
	v_fmamk_f32 v142, v142, 0x3a000000, v233
	ds_bpermute_b32 v154, v152, v140
	v_rsq_f32_e32 v153, v142
	ds_bpermute_b32 v156, v152, v140 offset:64
	ds_bpermute_b32 v150, v152, v140 offset:128
	ds_bpermute_b32 v148, v152, v140 offset:192
	ds_bpermute_b32 v146, v152, v153
	ds_bpermute_b32 v144, v152, v153 offset:64
	ds_bpermute_b32 v142, v152, v153 offset:128
	ds_bpermute_b32 v140, v152, v153 offset:192
	v_or_b32_e32 v153, s47, v141
	s_waitcnt lgkmcnt(0)
	v_pk_mul_f32 v[126:127], v[126:127], v[154:155] op_sel_hi:[1,0]
	v_pk_mul_f32 v[122:123], v[122:123], v[154:155] op_sel_hi:[1,0]
	v_pk_mul_f32 v[128:129], v[128:129], v[154:155] op_sel_hi:[1,0]
	v_pk_mul_f32 v[160:161], v[124:125], v[154:155] op_sel_hi:[1,0]
	v_cvt_pk_bf16_f32 v124, v126, v127
	v_cvt_pk_bf16_f32 v126, v122, v123
	v_mad_i64_i32 v[122:123], s[56:57], v153, s63, 0
	v_cvt_pk_bf16_f32 v125, v128, v129
	v_lshl_add_u64 v[128:129], v[122:123], 1, s[44:45]
	v_lshlrev_b64 v[122:123], 1, v[158:159]
	v_cvt_pk_bf16_f32 v127, v160, v161
	v_lshl_add_u64 v[128:129], v[128:129], 0, v[122:123]
	global_store_dwordx4 v[128:129], v[124:127], off
	v_pk_mul_f32 v[120:121], v[120:121], v[154:155] op_sel_hi:[1,0]
	v_pk_mul_f32 v[118:119], v[118:119], v[154:155] op_sel_hi:[1,0]
	v_pk_mul_f32 v[124:125], v[116:117], v[154:155] op_sel_hi:[1,0]
	v_pk_mul_f32 v[116:117], v[114:115], v[154:155] op_sel_hi:[1,0]
	v_cvt_pk_bf16_f32 v114, v118, v119
	v_cvt_pk_bf16_f32 v115, v120, v121
	v_cvt_pk_bf16_f32 v116, v116, v117
	v_cvt_pk_bf16_f32 v117, v124, v125
	global_store_dwordx4 v[128:129], v[114:117], off offset:256
	v_pk_mul_f32 v[110:111], v[110:111], v[156:157] op_sel_hi:[1,0]
	v_pk_mul_f32 v[112:113], v[112:113], v[156:157] op_sel_hi:[1,0]
	v_or_b32_e32 v116, 16, v153
	v_pk_mul_f32 v[114:115], v[108:109], v[156:157] op_sel_hi:[1,0]
	v_pk_mul_f32 v[108:109], v[106:107], v[156:157] op_sel_hi:[1,0]
	v_cvt_pk_bf16_f32 v106, v110, v111
	v_mad_i64_i32 v[110:111], s[56:57], v116, s63, 0
	v_lshl_add_u64 v[110:111], v[110:111], 1, s[44:45]
	v_cvt_pk_bf16_f32 v107, v112, v113
	v_cvt_pk_bf16_f32 v108, v108, v109
	v_cvt_pk_bf16_f32 v109, v114, v115
	v_lshl_add_u64 v[110:111], v[110:111], 0, v[122:123]
	global_store_dwordx4 v[110:111], v[106:109], off
	v_pk_mul_f32 v[104:105], v[104:105], v[156:157] op_sel_hi:[1,0]
	v_pk_mul_f32 v[102:103], v[102:103], v[156:157] op_sel_hi:[1,0]
	v_pk_mul_f32 v[106:107], v[100:101], v[156:157] op_sel_hi:[1,0]
	v_pk_mul_f32 v[100:101], v[98:99], v[156:157] op_sel_hi:[1,0]
	v_cvt_pk_bf16_f32 v98, v102, v103
	v_cvt_pk_bf16_f32 v99, v104, v105
	v_cvt_pk_bf16_f32 v100, v100, v101
	v_cvt_pk_bf16_f32 v101, v106, v107
	global_store_dwordx4 v[110:111], v[98:101], off offset:256
	v_pk_mul_f32 v[94:95], v[94:95], v[150:151] op_sel_hi:[1,0]
	v_pk_mul_f32 v[96:97], v[96:97], v[150:151] op_sel_hi:[1,0]
	v_or_b32_e32 v100, 32, v153
	v_pk_mul_f32 v[98:99], v[92:93], v[150:151] op_sel_hi:[1,0]
	v_pk_mul_f32 v[92:93], v[90:91], v[150:151] op_sel_hi:[1,0]
	v_cvt_pk_bf16_f32 v90, v94, v95
	v_mad_i64_i32 v[94:95], s[56:57], v100, s63, 0
	v_lshl_add_u64 v[94:95], v[94:95], 1, s[44:45]
	v_cvt_pk_bf16_f32 v91, v96, v97
	v_cvt_pk_bf16_f32 v92, v92, v93
	v_cvt_pk_bf16_f32 v93, v98, v99
	v_lshl_add_u64 v[94:95], v[94:95], 0, v[122:123]
	global_store_dwordx4 v[94:95], v[90:93], off
	v_pk_mul_f32 v[88:89], v[88:89], v[150:151] op_sel_hi:[1,0]
; __device__ __forceinline__ unsigned pk2(float lo, float hi) { f32x2 v = {lo, hi}; bf16x2_t b = __builtin_convertvector(v, bf16x2_t); return __builtin_bit_cast(unsigned, b); }
; #define PG8_WAIT_V(n) asm volatile("s_waitcnt vmcnt(" #n ")" ::: "memory")
; #define PG8_BAR __builtin_amdgcn_s_barrier()
;     __device__ __forceinline__ void operator()(const AccT& acc, const Unit& u, int wr, int wc, int fr, int fq) const {
;     ...
; #pragma unroll
;         for (int ai = 0; ai < 2; ++ai)
; #pragma unroll
;             for (int m = 0; m < 4; ++m) {
;                 const int row = row0 + ai * HALF + m * 16;
;                 const float rs = rsv[ai * 4 + m];
; #pragma unroll
;                 for (int bj = 0; bj < 2; ++bj) {
;                     const f32x4 v0 = acc[ai][bj][m][0] * rs, v1 = acc[ai][bj][m][1] * rs;
;                     u32x4 w; w.x = pk2(v0[0], v0[1]); w.y = pk2(v0[2], v0[3]); w.z = pk2(v1[0], v1[1]); w.w = pk2(v1[2], v1[3]);
;                     *(u32x4*)(out + (size_t)row * ldo + col0 + bj * HALF) = w;
;                 }
; template <class Epi>
; __device__ __forceinline__ void gemm_phase(LAS unsigned char* lds, const Gemm g, const StaticOrder& S, const Epi& E) {
;     ...
;         E(acc, cur, wr, wc, fr, fq);
;         if (!has_next) break;
; #pragma unroll
;         for (int a = 0; a < 2; ++a)
; #pragma unroll
;             for (int b = 0; b < 2; ++b)
; #pragma unroll
;                 for (int m = 0; m < 4; ++m)
; #pragma unroll
;                     for (int n = 0; n < 2; ++n) acc[a][b][m][n] = (f32x4){0.f, 0.f, 0.f, 0.f};
;         cur = nxt; cA = nA; cB = nB; ++ui;
;     }
;     PG8_WAIT_V(0);
;     if (wr == 0) PG8_BAR;
;     PG8_BAR;
	v_pk_mul_f32 v[86:87], v[86:87], v[150:151] op_sel_hi:[1,0]
	v_pk_mul_f32 v[90:91], v[84:85], v[150:151] op_sel_hi:[1,0]
	v_pk_mul_f32 v[84:85], v[82:83], v[150:151] op_sel_hi:[1,0]
	v_cvt_pk_bf16_f32 v82, v86, v87
	v_cvt_pk_bf16_f32 v83, v88, v89
	v_cvt_pk_bf16_f32 v84, v84, v85
	v_cvt_pk_bf16_f32 v85, v90, v91
	global_store_dwordx4 v[94:95], v[82:85], off offset:256
	v_pk_mul_f32 v[78:79], v[78:79], v[148:149] op_sel_hi:[1,0]
	v_pk_mul_f32 v[80:81], v[80:81], v[148:149] op_sel_hi:[1,0]
	v_or_b32_e32 v84, 48, v153
	v_pk_mul_f32 v[82:83], v[76:77], v[148:149] op_sel_hi:[1,0]
	v_pk_mul_f32 v[76:77], v[74:75], v[148:149] op_sel_hi:[1,0]
	v_cvt_pk_bf16_f32 v74, v78, v79
	v_mad_i64_i32 v[78:79], s[56:57], v84, s63, 0
	v_lshl_add_u64 v[78:79], v[78:79], 1, s[44:45]
	v_cvt_pk_bf16_f32 v75, v80, v81
	v_cvt_pk_bf16_f32 v76, v76, v77
	v_cvt_pk_bf16_f32 v77, v82, v83
	v_lshl_add_u64 v[78:79], v[78:79], 0, v[122:123]
	global_store_dwordx4 v[78:79], v[74:77], off
	v_pk_mul_f32 v[72:73], v[72:73], v[148:149] op_sel_hi:[1,0]
	v_pk_mul_f32 v[70:71], v[70:71], v[148:149] op_sel_hi:[1,0]
	v_pk_mul_f32 v[74:75], v[68:69], v[148:149] op_sel_hi:[1,0]
	v_pk_mul_f32 v[68:69], v[66:67], v[148:149] op_sel_hi:[1,0]
	v_cvt_pk_bf16_f32 v66, v70, v71
	v_cvt_pk_bf16_f32 v67, v72, v73
	v_cvt_pk_bf16_f32 v68, v68, v69
	v_cvt_pk_bf16_f32 v69, v74, v75
	global_store_dwordx4 v[78:79], v[66:69], off offset:256
	v_pk_mul_f32 v[62:63], v[62:63], v[146:147] op_sel_hi:[1,0]
	v_pk_mul_f32 v[64:65], v[64:65], v[146:147] op_sel_hi:[1,0]
	v_add_u32_e32 v68, 0x80, v153
	v_pk_mul_f32 v[66:67], v[60:61], v[146:147] op_sel_hi:[1,0]
	v_pk_mul_f32 v[60:61], v[58:59], v[146:147] op_sel_hi:[1,0]
	v_cvt_pk_bf16_f32 v58, v62, v63
	v_mad_i64_i32 v[62:63], s[56:57], v68, s63, 0
	v_lshl_add_u64 v[62:63], v[62:63], 1, s[44:45]
	v_cvt_pk_bf16_f32 v59, v64, v65
	v_cvt_pk_bf16_f32 v60, v60, v61
	v_cvt_pk_bf16_f32 v61, v66, v67
	v_lshl_add_u64 v[62:63], v[62:63], 0, v[122:123]
	global_store_dwordx4 v[62:63], v[58:61], off
	v_pk_mul_f32 v[52:53], v[52:53], v[146:147] op_sel_hi:[1,0]
	v_pk_mul_f32 v[50:51], v[50:51], v[146:147] op_sel_hi:[1,0]
	v_pk_mul_f32 v[58:59], v[44:45], v[146:147] op_sel_hi:[1,0]
	v_pk_mul_f32 v[44:45], v[42:43], v[146:147] op_sel_hi:[1,0]
	v_cvt_pk_bf16_f32 v42, v50, v51
	v_cvt_pk_bf16_f32 v43, v52, v53
	v_cvt_pk_bf16_f32 v44, v44, v45
	v_cvt_pk_bf16_f32 v45, v58, v59
	global_store_dwordx4 v[62:63], v[42:45], off offset:256
	v_add_u32_e32 v50, 0x90, v153
	v_pk_mul_f32 v[46:47], v[46:47], v[144:145] op_sel_hi:[1,0]
	v_pk_mul_f32 v[44:45], v[56:57], v[144:145] op_sel_hi:[1,0]
	v_pk_mul_f32 v[42:43], v[54:55], v[144:145] op_sel_hi:[1,0]
	v_pk_mul_f32 v[48:49], v[48:49], v[144:145] op_sel_hi:[1,0]
	v_cvt_pk_bf16_f32 v42, v42, v43
	v_cvt_pk_bf16_f32 v43, v44, v45
	v_cvt_pk_bf16_f32 v44, v46, v47
	v_mad_i64_i32 v[46:47], s[56:57], v50, s63, 0
	v_lshl_add_u64 v[46:47], v[46:47], 1, s[44:45]
	v_cvt_pk_bf16_f32 v45, v48, v49
	v_lshl_add_u64 v[46:47], v[46:47], 0, v[122:123]
	global_store_dwordx4 v[46:47], v[42:45], off
	v_pk_mul_f32 v[36:37], v[36:37], v[144:145] op_sel_hi:[1,0]
	v_pk_mul_f32 v[34:35], v[34:35], v[144:145] op_sel_hi:[1,0]
	v_pk_mul_f32 v[42:43], v[28:29], v[144:145] op_sel_hi:[1,0]
	v_pk_mul_f32 v[28:29], v[26:27], v[144:145] op_sel_hi:[1,0]
	v_cvt_pk_bf16_f32 v26, v34, v35
	v_cvt_pk_bf16_f32 v27, v36, v37
	v_cvt_pk_bf16_f32 v28, v28, v29
	v_cvt_pk_bf16_f32 v29, v42, v43
	global_store_dwordx4 v[46:47], v[26:29], off offset:256
	v_add_u32_e32 v34, 0xa0, v153
	v_pk_mul_f32 v[30:31], v[30:31], v[142:143] op_sel_hi:[1,0]
	v_pk_mul_f32 v[28:29], v[40:41], v[142:143] op_sel_hi:[1,0]
	v_pk_mul_f32 v[26:27], v[38:39], v[142:143] op_sel_hi:[1,0]
	v_pk_mul_f32 v[32:33], v[32:33], v[142:143] op_sel_hi:[1,0]
	v_cvt_pk_bf16_f32 v26, v26, v27
	v_cvt_pk_bf16_f32 v27, v28, v29
	v_cvt_pk_bf16_f32 v28, v30, v31
	v_mad_i64_i32 v[30:31], s[56:57], v34, s63, 0
	v_lshl_add_u64 v[30:31], v[30:31], 1, s[44:45]
	v_cvt_pk_bf16_f32 v29, v32, v33
	v_lshl_add_u64 v[30:31], v[30:31], 0, v[122:123]
	global_store_dwordx4 v[30:31], v[26:29], off
	v_pk_mul_f32 v[20:21], v[20:21], v[142:143] op_sel_hi:[1,0]
	v_pk_mul_f32 v[18:19], v[18:19], v[142:143] op_sel_hi:[1,0]
	v_pk_mul_f32 v[26:27], v[12:13], v[142:143] op_sel_hi:[1,0]
	v_pk_mul_f32 v[12:13], v[10:11], v[142:143] op_sel_hi:[1,0]
	v_cvt_pk_bf16_f32 v10, v18, v19
	v_cvt_pk_bf16_f32 v11, v20, v21
	v_cvt_pk_bf16_f32 v12, v12, v13
	v_cvt_pk_bf16_f32 v13, v26, v27
	global_store_dwordx4 v[30:31], v[10:13], off offset:256
	v_add_u32_e32 v18, 0xb0, v153
	v_pk_mul_f32 v[14:15], v[14:15], v[140:141] op_sel_hi:[1,0]
	v_pk_mul_f32 v[12:13], v[24:25], v[140:141] op_sel_hi:[1,0]
	v_pk_mul_f32 v[10:11], v[22:23], v[140:141] op_sel_hi:[1,0]
	v_pk_mul_f32 v[16:17], v[16:17], v[140:141] op_sel_hi:[1,0]
	v_cvt_pk_bf16_f32 v10, v10, v11
	v_cvt_pk_bf16_f32 v11, v12, v13
	v_cvt_pk_bf16_f32 v12, v14, v15
	v_mad_i64_i32 v[14:15], s[56:57], v18, s63, 0
	v_lshl_add_u64 v[14:15], v[14:15], 1, s[44:45]
	v_cvt_pk_bf16_f32 v13, v16, v17
	v_lshl_add_u64 v[14:15], v[14:15], 0, v[122:123]
	global_store_dwordx4 v[14:15], v[10:13], off
	v_pk_mul_f32 v[8:9], v[8:9], v[140:141] op_sel_hi:[1,0]
	v_pk_mul_f32 v[6:7], v[6:7], v[140:141] op_sel_hi:[1,0]
	v_pk_mul_f32 v[10:11], v[4:5], v[140:141] op_sel_hi:[1,0]
	v_pk_mul_f32 v[4:5], v[2:3], v[140:141] op_sel_hi:[1,0]
	v_cvt_pk_bf16_f32 v2, v6, v7
	v_cvt_pk_bf16_f32 v3, v8, v9
	v_cvt_pk_bf16_f32 v4, v4, v5
	v_cvt_pk_bf16_f32 v5, v10, v11
	s_mov_b64 s[56:57], s[50:51]
	global_store_dwordx4 v[14:15], v[2:5], off offset:256
	s_cbranch_vccz .LBB0_61
	s_waitcnt vmcnt(0)
	s_cmpk_gt_u32 s64, 0xff
	s_cbranch_scc1 .LBB0_68
	s_barrier

; #define PG8_STAGE(bufoff, gbase, voff) do { _Pragma("unroll") for (int _i = 0; _i < 2; ++_i) \
;         __builtin_amdgcn_global_load_lds((const unsigned*)((const char*)(gbase) + (voff)[_i]), (LAS unsigned*)(lds + (bufoff) + ldsw + _i * 8192), 16, 0, 0); } while (0)
; #define PG8_LDA(dst, b, h) do { _Pragma("unroll") for (int m = 0; m < 4; ++m) _Pragma("unroll") for (int k = 0; k < 2; ++k) dst[m][k] = *(const LAS bf16x8*)(lds + PG8_SA(b, h) + aoff + m * 2048 + k * 1024); } while (0)
; #define PG8_LDB(dst, b, h) do { _Pragma("unroll") for (int n = 0; n < 2; ++n) _Pragma("unroll") for (int k = 0; k < 2; ++k) dst[n][k] = *(const LAS bf16x8*)(lds + PG8_SB(b, h) + boff + n * 2048 + k * 1024); } while (0)
; #define PG8_MMA(ai, bj, At, Bt) do { __builtin_amdgcn_s_setprio(1); _Pragma("unroll") for (int m = 0; m < 4; ++m) _Pragma("unroll") for (int n = 0; n < 2; ++n) _Pragma("unroll") for (int k = 0; k < 2; ++k) \
;         acc[ai][bj][m][n] = __builtin_amdgcn_mfma_f32_16x16x32_bf16(Bt[n][k], At[m][k], acc[ai][bj][m][n], 0, 0, 0); __builtin_amdgcn_s_setprio(0); } while (0)
; #define PG8_WAIT_V(n) asm volatile("s_waitcnt vmcnt(" #n ")" ::: "memory")
; template <class Epi>
; __device__ __forceinline__ void gemm_phase(LAS unsigned char* lds, const Gemm g, const StaticOrder& S, const Epi& E) {
;     ...
;         for (int t = 0; t < nt; t += 2) {
;             const bool last = (t == nt - 2);
;             const char* a1 = cA + (size_t)(t + 1) * kstep;
;             const char* a2 = last ? nA : cA + (size_t)(t + 2) * kstep; const char* b2 = last ? nB : cB + (size_t)(t + 2) * kstep;
;             const char* a3 = a2 + kstep; const char* b3 = b2 + kstep;
;             PG8_LDB(B0, 0, 0); PG8_SCHED; PG8_LDA(At, 0, 0); PG8_STAGE(PG8_SA(1, 1), a1 + hstep, voffA);
;             PG8_WAIT_L(8); PG8_BAR; PG8_WAIT_L(0); PG8_MMA(0, 0, At, B0); PG8_BAR; PG8_SCHED;
;             PG8_LDB(B1, 0, 1); PG8_STAGE(PG8_SB(0, 0), b2, voffB);
;             PG8_BAR; PG8_WAIT_L(0); PG8_MMA(0, 1, At, B1); PG8_BAR;
;             PG8_LDA(At, 0, 1); PG8_STAGE(PG8_SA(0, 0), a2, voffA);
;             PG8_BAR; PG8_WAIT_L(0); PG8_MMA(1, 0, At, B0); PG8_BAR; PG8_SCHED;
;             PG8_STAGE(PG8_SB(0, 1), b2 + hstep, voffB);
;             PG8_WAIT_V(6); PG8_BAR; PG8_MMA(1, 1, At, B1); PG8_BAR;
;             PG8_LDB(B0, 1, 0); PG8_SCHED; PG8_LDA(At, 1, 0); PG8_STAGE(PG8_SA(0, 1), a2 + hstep, voffA);
.LBB0_77:
	s_add_u32 s56, s54, 0xfff80080
	s_addc_u32 s57, s55, -1
	s_add_i32 s81, 0, 0x10000
	s_cmp_eq_u32 s80, 28
	s_cselect_b32 s59, s49, s57
	s_cselect_b32 s58, s76, s56
	s_cselect_b32 s57, s47, s79
	s_cselect_b32 s56, s77, s78
	s_add_i32 m0, s65, 0xc000
	ds_read_b128 v[160:163], v143
	ds_read_b128 v[164:167], v143 offset:1024
	ds_read_b128 v[168:171], v143 offset:2048
	ds_read_b128 v[172:175], v143 offset:3072
	ds_read_b128 v[176:179], v143 offset:4096
	ds_read_b128 v[180:183], v143 offset:5120
	ds_read_b128 v[184:187], v143 offset:6144
	ds_read_b128 v[188:191], v143 offset:7168
	global_load_lds_dwordx4 v136, s[54:55]
	s_add_i32 m0, s65, 0xe000
	s_waitcnt lgkmcnt(8)
	global_load_lds_dwordx4 v138, s[54:55]
	s_barrier
	s_waitcnt lgkmcnt(0)
	v_mfma_f32_16x16x32_bf16 v[126:129], v[144:147], v[160:163], v[126:129]
	v_mfma_f32_16x16x32_bf16 v[122:125], v[152:155], v[160:163], v[122:125]
	v_mfma_f32_16x16x32_bf16 v[118:121], v[144:147], v[168:171], v[118:121]
	v_mfma_f32_16x16x32_bf16 v[114:117], v[152:155], v[168:171], v[114:117]
	v_mfma_f32_16x16x32_bf16 v[102:105], v[144:147], v[176:179], v[102:105]
	v_mfma_f32_16x16x32_bf16 v[98:101], v[152:155], v[176:179], v[98:101]
	v_mfma_f32_16x16x32_bf16 v[86:89], v[144:147], v[184:187], v[86:89]
	v_mfma_f32_16x16x32_bf16 v[82:85], v[152:155], v[184:187], v[82:85]
	v_mfma_f32_16x16x32_bf16 v[126:129], v[148:151], v[164:167], v[126:129]
	v_mfma_f32_16x16x32_bf16 v[122:125], v[156:159], v[164:167], v[122:125]
	v_mfma_f32_16x16x32_bf16 v[118:121], v[148:151], v[172:175], v[118:121]
	v_mfma_f32_16x16x32_bf16 v[114:117], v[156:159], v[172:175], v[114:117]
	v_mfma_f32_16x16x32_bf16 v[102:105], v[148:151], v[180:183], v[102:105]
	v_mfma_f32_16x16x32_bf16 v[98:101], v[156:159], v[180:183], v[98:101]
	v_mfma_f32_16x16x32_bf16 v[86:89], v[148:151], v[188:191], v[86:89]
	v_mfma_f32_16x16x32_bf16 v[82:85], v[156:159], v[188:191], v[82:85]
	s_barrier
	s_add_i32 s81, s81, s64
	ds_read_b128 v[192:195], v202 offset:16384
	ds_read_b128 v[196:199], v202 offset:17408
	ds_read_b128 v[208:211], v202 offset:18432
	ds_read_b128 v[212:215], v202 offset:19456
	s_mov_b32 m0, s81
	s_add_u32 s98, s56, s22
	s_addc_u32 s99, s57, s23
	global_load_lds_dwordx4 v0, s[56:57]
	s_add_i32 m0, s81, 0x2000
	s_add_i32 s84, 0, 0x14000
	global_load_lds_dwordx4 v130, s[56:57]
	s_barrier
	s_waitcnt lgkmcnt(0)
	v_mfma_f32_16x16x32_bf16 v[110:113], v[192:195], v[160:163], v[110:113]
	v_mfma_f32_16x16x32_bf16 v[106:109], v[208:211], v[160:163], v[106:109]
	v_mfma_f32_16x16x32_bf16 v[94:97], v[192:195], v[168:171], v[94:97]
	v_mfma_f32_16x16x32_bf16 v[90:93], v[208:211], v[168:171], v[90:93]
	v_mfma_f32_16x16x32_bf16 v[78:81], v[192:195], v[176:179], v[78:81]
	v_mfma_f32_16x16x32_bf16 v[74:77], v[208:211], v[176:179], v[74:77]
	v_mfma_f32_16x16x32_bf16 v[70:73], v[192:195], v[184:187], v[70:73]
	v_mfma_f32_16x16x32_bf16 v[66:69], v[208:211], v[184:187], v[66:69]
	v_mfma_f32_16x16x32_bf16 v[110:113], v[196:199], v[164:167], v[110:113]
	v_mfma_f32_16x16x32_bf16 v[106:109], v[212:215], v[164:167], v[106:109]
	v_mfma_f32_16x16x32_bf16 v[94:97], v[196:199], v[172:175], v[94:97]
	v_mfma_f32_16x16x32_bf16 v[90:93], v[212:215], v[172:175], v[90:93]
	v_mfma_f32_16x16x32_bf16 v[78:81], v[196:199], v[180:183], v[78:81]
	v_mfma_f32_16x16x32_bf16 v[74:77], v[212:215], v[180:183], v[74:77]
	v_mfma_f32_16x16x32_bf16 v[70:73], v[196:199], v[188:191], v[70:73]
	v_mfma_f32_16x16x32_bf16 v[66:69], v[212:215], v[188:191], v[66:69]
	s_barrier
	ds_read_b128 v[160:163], v143 offset:16384
	ds_read_b128 v[164:167], v143 offset:17408
	ds_read_b128 v[168:171], v143 offset:18432
	ds_read_b128 v[172:175], v143 offset:19456
	ds_read_b128 v[176:179], v143 offset:20480
	ds_read_b128 v[180:183], v143 offset:21504
	ds_read_b128 v[184:187], v143 offset:22528
	s_mov_b32 m0, s65
	s_add_u32 s100, s58, s22
	s_addc_u32 s101, s59, s23
	ds_read_b128 v[188:191], v143 offset:23552
	global_load_lds_dwordx4 v134, s[58:59]
	s_mov_b32 m0, s68
	s_waitcnt vmcnt(9)
	global_load_lds_dwordx4 v132, s[58:59]
	s_barrier
	s_waitcnt lgkmcnt(0)
	v_mfma_f32_16x16x32_bf16 v[62:65], v[144:147], v[160:163], v[62:65]
	v_mfma_f32_16x16x32_bf16 v[58:61], v[152:155], v[160:163], v[58:61]
	v_mfma_f32_16x16x32_bf16 v[54:57], v[144:147], v[168:171], v[54:57]
	v_mfma_f32_16x16x32_bf16 v[50:53], v[152:155], v[168:171], v[50:53]
	v_mfma_f32_16x16x32_bf16 v[38:41], v[144:147], v[176:179], v[38:41]
	v_mfma_f32_16x16x32_bf16 v[34:37], v[152:155], v[176:179], v[34:37]
	v_mfma_f32_16x16x32_bf16 v[22:25], v[144:147], v[184:187], v[22:25]
	v_mfma_f32_16x16x32_bf16 v[18:21], v[152:155], v[184:187], v[18:21]
	v_mfma_f32_16x16x32_bf16 v[62:65], v[148:151], v[164:167], v[62:65]
	v_mfma_f32_16x16x32_bf16 v[58:61], v[156:159], v[164:167], v[58:61]
	v_mfma_f32_16x16x32_bf16 v[54:57], v[148:151], v[172:175], v[54:57]
	v_mfma_f32_16x16x32_bf16 v[50:53], v[156:159], v[172:175], v[50:53]
	v_mfma_f32_16x16x32_bf16 v[38:41], v[148:151], v[180:183], v[38:41]
	v_mfma_f32_16x16x32_bf16 v[34:37], v[156:159], v[180:183], v[34:37]
	v_mfma_f32_16x16x32_bf16 v[22:25], v[148:151], v[188:191], v[22:25]
	v_mfma_f32_16x16x32_bf16 v[18:21], v[156:159], v[188:191], v[18:21]
	s_barrier
	ds_read_b128 v[144:147], v202 offset:32768
	ds_read_b128 v[148:151], v202 offset:33792
	ds_read_b128 v[152:155], v202 offset:34816
	ds_read_b128 v[156:159], v202 offset:35840
	s_add_i32 s81, s84, s64
	s_mov_b32 m0, s81
	s_add_u32 s82, s56, 0x80000
	s_addc_u32 s83, s57, 0
	global_load_lds_dwordx4 v0, s[82:83]
	s_add_i32 m0, s81, 0x2000
	s_waitcnt vmcnt(5)
	global_load_lds_dwordx4 v130, s[82:83]
	s_barrier
; #define PG8_STAGE(bufoff, gbase, voff) do { _Pragma("unroll") for (int _i = 0; _i < 2; ++_i) \
;         __builtin_amdgcn_global_load_lds((const unsigned*)((const char*)(gbase) + (voff)[_i]), (LAS unsigned*)(lds + (bufoff) + ldsw + _i * 8192), 16, 0, 0); } while (0)
; #define PG8_LDA(dst, b, h) do { _Pragma("unroll") for (int m = 0; m < 4; ++m) _Pragma("unroll") for (int k = 0; k < 2; ++k) dst[m][k] = *(const LAS bf16x8*)(lds + PG8_SA(b, h) + aoff + m * 2048 + k * 1024); } while (0)
; #define PG8_LDB(dst, b, h) do { _Pragma("unroll") for (int n = 0; n < 2; ++n) _Pragma("unroll") for (int k = 0; k < 2; ++k) dst[n][k] = *(const LAS bf16x8*)(lds + PG8_SB(b, h) + boff + n * 2048 + k * 1024); } while (0)
; #define PG8_MMA(ai, bj, At, Bt) do { __builtin_amdgcn_s_setprio(1); _Pragma("unroll") for (int m = 0; m < 4; ++m) _Pragma("unroll") for (int n = 0; n < 2; ++n) _Pragma("unroll") for (int k = 0; k < 2; ++k) \
;         acc[ai][bj][m][n] = __builtin_amdgcn_mfma_f32_16x16x32_bf16(Bt[n][k], At[m][k], acc[ai][bj][m][n], 0, 0, 0); __builtin_amdgcn_s_setprio(0); } while (0)
; #define PG8_WAIT_V(n) asm volatile("s_waitcnt vmcnt(" #n ")" ::: "memory")
; #define PG8_WAIT_L(n) asm volatile("s_waitcnt lgkmcnt(" #n ")" ::: "memory")
; #define PG8_BAR __builtin_amdgcn_s_barrier()
; #define PG8_SCHED __builtin_amdgcn_sched_barrier(0)
; template <class Epi>
; __device__ __forceinline__ void gemm_phase(LAS unsigned char* lds, const Gemm g, const StaticOrder& S, const Epi& E) {
;     ...
;             PG8_LDB(B0, 1, 0); PG8_SCHED; PG8_LDA(At, 1, 0); PG8_STAGE(PG8_SA(0, 1), a2 + hstep, voffA);
;             PG8_WAIT_L(8); PG8_BAR; PG8_WAIT_L(0); PG8_MMA(0, 0, At, B0); PG8_BAR; PG8_SCHED;
;             PG8_LDB(B1, 1, 1); PG8_STAGE(PG8_SB(1, 0), b3, voffB);
;             PG8_BAR; PG8_WAIT_L(0); PG8_MMA(0, 1, At, B1); PG8_BAR;
;             PG8_LDA(At, 1, 1); PG8_STAGE(PG8_SA(1, 0), a3, voffA);
;             PG8_BAR; PG8_WAIT_L(0); PG8_MMA(1, 0, At, B0); PG8_BAR; PG8_SCHED;
;             PG8_STAGE(PG8_SB(1, 1), b3 + hstep, voffB);
;             PG8_WAIT_V(6); PG8_BAR; PG8_MMA(1, 1, At, B1); PG8_BAR;
	v_mfma_f32_16x16x32_bf16 v[46:49], v[192:195], v[160:163], v[46:49]
	v_mfma_f32_16x16x32_bf16 v[42:45], v[208:211], v[160:163], v[42:45]
	v_mfma_f32_16x16x32_bf16 v[30:33], v[192:195], v[168:171], v[30:33]
	v_mfma_f32_16x16x32_bf16 v[26:29], v[208:211], v[168:171], v[26:29]
	v_mfma_f32_16x16x32_bf16 v[14:17], v[192:195], v[176:179], v[14:17]
	v_mfma_f32_16x16x32_bf16 v[10:13], v[208:211], v[176:179], v[10:13]
	v_mfma_f32_16x16x32_bf16 v[6:9], v[192:195], v[184:187], v[6:9]
	v_mfma_f32_16x16x32_bf16 v[2:5], v[208:211], v[184:187], v[2:5]
	v_mfma_f32_16x16x32_bf16 v[46:49], v[196:199], v[164:167], v[46:49]
	v_mfma_f32_16x16x32_bf16 v[42:45], v[212:215], v[164:167], v[42:45]
	v_mfma_f32_16x16x32_bf16 v[30:33], v[196:199], v[172:175], v[30:33]
	v_mfma_f32_16x16x32_bf16 v[26:29], v[212:215], v[172:175], v[26:29]
	v_mfma_f32_16x16x32_bf16 v[14:17], v[196:199], v[180:183], v[14:17]
	v_mfma_f32_16x16x32_bf16 v[10:13], v[212:215], v[180:183], v[10:13]
	v_mfma_f32_16x16x32_bf16 v[6:9], v[196:199], v[188:191], v[6:9]
	v_mfma_f32_16x16x32_bf16 v[2:5], v[212:215], v[188:191], v[2:5]
	s_barrier
	s_add_u32 s58, s58, 0x80000
	s_addc_u32 s59, s59, 0
	s_mov_b32 m0, s69
	ds_read_b128 v[160:163], v143 offset:32768
	ds_read_b128 v[164:167], v143 offset:33792
	ds_read_b128 v[168:171], v143 offset:34816
	ds_read_b128 v[172:175], v143 offset:35840
	ds_read_b128 v[176:179], v143 offset:36864
	ds_read_b128 v[180:183], v143 offset:37888
	ds_read_b128 v[184:187], v143 offset:38912
	s_add_i32 s81, 0, 0x18000
	ds_read_b128 v[188:191], v143 offset:39936
	global_load_lds_dwordx4 v134, s[58:59]
	s_mov_b32 m0, s70
	s_waitcnt lgkmcnt(8)
	global_load_lds_dwordx4 v132, s[58:59]
	s_barrier
	s_waitcnt lgkmcnt(0)
	v_mfma_f32_16x16x32_bf16 v[126:129], v[144:147], v[160:163], v[126:129]
	v_mfma_f32_16x16x32_bf16 v[122:125], v[152:155], v[160:163], v[122:125]
	v_mfma_f32_16x16x32_bf16 v[118:121], v[144:147], v[168:171], v[118:121]
	v_mfma_f32_16x16x32_bf16 v[114:117], v[152:155], v[168:171], v[114:117]
	v_mfma_f32_16x16x32_bf16 v[102:105], v[144:147], v[176:179], v[102:105]
	v_mfma_f32_16x16x32_bf16 v[98:101], v[152:155], v[176:179], v[98:101]
	v_mfma_f32_16x16x32_bf16 v[86:89], v[144:147], v[184:187], v[86:89]
	v_mfma_f32_16x16x32_bf16 v[82:85], v[152:155], v[184:187], v[82:85]
	v_mfma_f32_16x16x32_bf16 v[126:129], v[148:151], v[164:167], v[126:129]
	v_mfma_f32_16x16x32_bf16 v[122:125], v[156:159], v[164:167], v[122:125]
	v_mfma_f32_16x16x32_bf16 v[118:121], v[148:151], v[172:175], v[118:121]
	v_mfma_f32_16x16x32_bf16 v[114:117], v[156:159], v[172:175], v[114:117]
	v_mfma_f32_16x16x32_bf16 v[102:105], v[148:151], v[180:183], v[102:105]
	v_mfma_f32_16x16x32_bf16 v[98:101], v[156:159], v[180:183], v[98:101]
	v_mfma_f32_16x16x32_bf16 v[86:89], v[148:151], v[188:191], v[86:89]
	v_mfma_f32_16x16x32_bf16 v[82:85], v[156:159], v[188:191], v[82:85]
	s_barrier
	s_add_i32 s59, s81, s64
	s_mov_b32 m0, s59
	ds_read_b128 v[192:195], v202 offset:49152
	ds_read_b128 v[196:199], v202 offset:50176
	ds_read_b128 v[208:211], v202 offset:51200
	ds_read_b128 v[212:215], v202 offset:52224
	global_load_lds_dwordx4 v0, s[98:99]
	s_add_i32 m0, s59, 0x2000
	s_add_i32 s58, 0, 0x1c000
	global_load_lds_dwordx4 v130, s[98:99]
	s_barrier
	s_waitcnt lgkmcnt(0)
	v_mfma_f32_16x16x32_bf16 v[110:113], v[192:195], v[160:163], v[110:113]
	v_mfma_f32_16x16x32_bf16 v[106:109], v[208:211], v[160:163], v[106:109]
	v_mfma_f32_16x16x32_bf16 v[94:97], v[192:195], v[168:171], v[94:97]
	v_mfma_f32_16x16x32_bf16 v[90:93], v[208:211], v[168:171], v[90:93]
	v_mfma_f32_16x16x32_bf16 v[78:81], v[192:195], v[176:179], v[78:81]
	v_mfma_f32_16x16x32_bf16 v[74:77], v[208:211], v[176:179], v[74:77]
	v_mfma_f32_16x16x32_bf16 v[70:73], v[192:195], v[184:187], v[70:73]
	v_mfma_f32_16x16x32_bf16 v[66:69], v[208:211], v[184:187], v[66:69]
	v_mfma_f32_16x16x32_bf16 v[110:113], v[196:199], v[164:167], v[110:113]
	v_mfma_f32_16x16x32_bf16 v[106:109], v[212:215], v[164:167], v[106:109]
	v_mfma_f32_16x16x32_bf16 v[94:97], v[196:199], v[172:175], v[94:97]
	v_mfma_f32_16x16x32_bf16 v[90:93], v[212:215], v[172:175], v[90:93]
	v_mfma_f32_16x16x32_bf16 v[78:81], v[196:199], v[180:183], v[78:81]
	v_mfma_f32_16x16x32_bf16 v[74:77], v[212:215], v[180:183], v[74:77]
	v_mfma_f32_16x16x32_bf16 v[70:73], v[196:199], v[188:191], v[70:73]
	v_mfma_f32_16x16x32_bf16 v[66:69], v[212:215], v[188:191], v[66:69]
	s_barrier
	ds_read_b128 v[160:163], v143 offset:49152
	ds_read_b128 v[164:167], v143 offset:50176
	ds_read_b128 v[168:171], v143 offset:51200
	ds_read_b128 v[172:175], v143 offset:52224
	ds_read_b128 v[176:179], v143 offset:53248
	ds_read_b128 v[180:183], v143 offset:54272
	ds_read_b128 v[184:187], v143 offset:55296
	s_mov_b32 m0, s71
	ds_read_b128 v[188:191], v143 offset:56320
	global_load_lds_dwordx4 v134, s[100:101]
	s_mov_b32 m0, s72
	s_waitcnt vmcnt(9)
	global_load_lds_dwordx4 v132, s[100:101]
	s_barrier
	s_waitcnt lgkmcnt(0)
	v_mfma_f32_16x16x32_bf16 v[62:65], v[144:147], v[160:163], v[62:65]
	v_mfma_f32_16x16x32_bf16 v[58:61], v[152:155], v[160:163], v[58:61]
	v_mfma_f32_16x16x32_bf16 v[54:57], v[144:147], v[168:171], v[54:57]
	v_mfma_f32_16x16x32_bf16 v[50:53], v[152:155], v[168:171], v[50:53]
	v_mfma_f32_16x16x32_bf16 v[38:41], v[144:147], v[176:179], v[38:41]
	v_mfma_f32_16x16x32_bf16 v[34:37], v[152:155], v[176:179], v[34:37]
	v_mfma_f32_16x16x32_bf16 v[22:25], v[144:147], v[184:187], v[22:25]
	v_mfma_f32_16x16x32_bf16 v[18:21], v[152:155], v[184:187], v[18:21]
	v_mfma_f32_16x16x32_bf16 v[62:65], v[148:151], v[164:167], v[62:65]
	v_mfma_f32_16x16x32_bf16 v[58:61], v[156:159], v[164:167], v[58:61]
	v_mfma_f32_16x16x32_bf16 v[54:57], v[148:151], v[172:175], v[54:57]
	v_mfma_f32_16x16x32_bf16 v[50:53], v[156:159], v[172:175], v[50:53]
	v_mfma_f32_16x16x32_bf16 v[38:41], v[148:151], v[180:183], v[38:41]
	v_mfma_f32_16x16x32_bf16 v[34:37], v[156:159], v[180:183], v[34:37]
	v_mfma_f32_16x16x32_bf16 v[22:25], v[148:151], v[188:191], v[22:25]
	v_mfma_f32_16x16x32_bf16 v[18:21], v[156:159], v[188:191], v[18:21]
	s_barrier
; __device__ __forceinline__ unsigned pk2(float lo, float hi) { f32x2 v = {lo, hi}; bf16x2_t b = __builtin_convertvector(v, bf16x2_t); return __builtin_bit_cast(unsigned, b); }
; #define PG8_MMA(ai, bj, At, Bt) do { __builtin_amdgcn_s_setprio(1); _Pragma("unroll") for (int m = 0; m < 4; ++m) _Pragma("unroll") for (int n = 0; n < 2; ++n) _Pragma("unroll") for (int k = 0; k < 2; ++k) \
;         acc[ai][bj][m][n] = __builtin_amdgcn_mfma_f32_16x16x32_bf16(Bt[n][k], At[m][k], acc[ai][bj][m][n], 0, 0, 0); __builtin_amdgcn_s_setprio(0); } while (0)
; #define PG8_WAIT_V(n) asm volatile("s_waitcnt vmcnt(" #n ")" ::: "memory")
; #define PG8_BAR __builtin_amdgcn_s_barrier()
;     __device__ __forceinline__ void operator()(const AccT& acc, const Unit& u, int wr, int wc, int fr, int fq) const {
;     ...
; #pragma unroll
;         for (int ai = 0; ai < 2; ++ai)
; #pragma unroll
;             for (int m = 0; m < 4; ++m) {
;                 const int row = row0 + ai * HALF + m * 16;
;                 const float rs = rsv[ai * 4 + m];
; #pragma unroll
;                 for (int bj = 0; bj < 2; ++bj) {
;                     const f32x4 v0 = acc[ai][bj][m][0] * rs, v1 = acc[ai][bj][m][1] * rs;
;                     u32x4 w; w.x = pk2(v0[0], v0[1]); w.y = pk2(v0[2], v0[3]); w.z = pk2(v1[0], v1[1]); w.w = pk2(v1[2], v1[3]);
;                     *(u32x4*)(out + (size_t)row * ldo + col0 + bj * HALF) = w;
;                 }
; template <class Epi>
; __device__ __forceinline__ void gemm_phase(LAS unsigned char* lds, const Gemm g, const StaticOrder& S, const Epi& E) {
;     ...
;             PG8_WAIT_V(6); PG8_BAR; PG8_MMA(1, 1, At, B1); PG8_BAR;
;         }
;         E(acc, cur, wr, wc, fr, fq);
	ds_read_b128 v[144:147], v202
	ds_read_b128 v[148:151], v202 offset:1024
	ds_read_b128 v[152:155], v202 offset:2048
	s_add_i32 s80, s80, 2
	s_add_u32 s54, s54, 0x100
	s_addc_u32 s55, s55, 0
	s_add_u32 s78, s78, 0x100
	s_addc_u32 s79, s79, 0
	ds_read_b128 v[156:159], v202 offset:3072
	s_add_i32 s58, s58, s64
	s_mov_b32 m0, s58
	s_add_u32 s56, s56, 0x80080
	s_addc_u32 s57, s57, 0
	global_load_lds_dwordx4 v0, s[56:57]
	s_add_i32 m0, s58, 0x2000
	s_waitcnt vmcnt(5)
	global_load_lds_dwordx4 v130, s[56:57]
	s_barrier
	v_mfma_f32_16x16x32_bf16 v[46:49], v[192:195], v[160:163], v[46:49]
	v_mfma_f32_16x16x32_bf16 v[42:45], v[208:211], v[160:163], v[42:45]
	v_mfma_f32_16x16x32_bf16 v[30:33], v[192:195], v[168:171], v[30:33]
	v_mfma_f32_16x16x32_bf16 v[26:29], v[208:211], v[168:171], v[26:29]
	v_mfma_f32_16x16x32_bf16 v[14:17], v[192:195], v[176:179], v[14:17]
	v_mfma_f32_16x16x32_bf16 v[10:13], v[208:211], v[176:179], v[10:13]
	v_mfma_f32_16x16x32_bf16 v[6:9], v[192:195], v[184:187], v[6:9]
	v_mfma_f32_16x16x32_bf16 v[2:5], v[208:211], v[184:187], v[2:5]
	v_mfma_f32_16x16x32_bf16 v[46:49], v[196:199], v[164:167], v[46:49]
	v_mfma_f32_16x16x32_bf16 v[42:45], v[212:215], v[164:167], v[42:45]
	v_mfma_f32_16x16x32_bf16 v[30:33], v[196:199], v[172:175], v[30:33]
	v_mfma_f32_16x16x32_bf16 v[26:29], v[212:215], v[172:175], v[26:29]
	v_mfma_f32_16x16x32_bf16 v[14:17], v[196:199], v[180:183], v[14:17]
	v_mfma_f32_16x16x32_bf16 v[10:13], v[212:215], v[180:183], v[10:13]
	v_mfma_f32_16x16x32_bf16 v[6:9], v[196:199], v[188:191], v[6:9]
	v_mfma_f32_16x16x32_bf16 v[2:5], v[212:215], v[188:191], v[2:5]
	s_cmp_gt_u32 s80, 29
	s_barrier
	s_cbranch_scc0 .LBB0_77
	s_waitcnt lgkmcnt(0)
	v_lshl_add_u32 v146, s74, 8, v140
	v_lshl_or_b32 v144, s75, 8, v142
	v_ashrrev_i32_e32 v147, 31, v146
	v_ashrrev_i32_e32 v145, 31, v144
	v_cvt_pk_bf16_f32 v126, v126, v127
	v_cvt_pk_bf16_f32 v127, v128, v129
	v_cvt_pk_bf16_f32 v128, v122, v123
	v_lshlrev_b64 v[122:123], 11, v[146:147]
	v_cvt_pk_bf16_f32 v129, v124, v125
	v_lshl_add_u64 v[122:123], s[42:43], 0, v[122:123]
	v_lshlrev_b64 v[124:125], 1, v[144:145]
	v_lshl_add_u64 v[122:123], v[122:123], 0, v[124:125]
	v_cvt_pk_bf16_f32 v110, v110, v111
	v_cvt_pk_bf16_f32 v111, v112, v113
	v_cvt_pk_bf16_f32 v112, v106, v107
	v_cvt_pk_bf16_f32 v113, v108, v109
	global_store_dwordx4 v[122:123], v[110:113], off offset:256
	v_cvt_pk_bf16_f32 v94, v94, v95
	v_cvt_pk_bf16_f32 v95, v96, v97
	v_or_b32_e32 v110, 16, v146
	v_ashrrev_i32_e32 v111, 31, v110
	v_lshlrev_b64 v[110:111], 11, v[110:111]
	v_lshl_add_u64 v[110:111], s[42:43], 0, v[110:111]
	v_lshl_add_u64 v[110:111], v[110:111], 0, v[124:125]
	v_cvt_pk_bf16_f32 v96, v90, v91
	v_cvt_pk_bf16_f32 v97, v92, v93
	global_store_dwordx4 v[110:111], v[94:97], off offset:256
	s_mov_b32 s47, 0x40000
	v_cvt_pk_bf16_f32 v62, v62, v63
	v_or_b32_e32 v94, 32, v146
	v_ashrrev_i32_e32 v95, 31, v94
	v_cvt_pk_bf16_f32 v63, v64, v65
	v_cvt_pk_bf16_f32 v65, v60, v61
	s_mov_b64 s[54:55], 0x40000
	v_add_co_u32_e32 v60, vcc, s47, v122
	v_lshlrev_b64 v[94:95], 11, v[94:95]
	v_cvt_pk_bf16_f32 v64, v58, v59
	v_lshl_add_u64 v[58:59], v[122:123], 0, s[54:55]
	v_addc_co_u32_e32 v61, vcc, 0, v123, vcc
	v_cvt_pk_bf16_f32 v46, v46, v47
	v_cvt_pk_bf16_f32 v47, v48, v49
	v_cvt_pk_bf16_f32 v48, v42, v43
	v_cvt_pk_bf16_f32 v49, v44, v45
	s_mov_b32 s47, 0x48000
	v_lshl_add_u64 v[94:95], s[42:43], 0, v[94:95]
	global_store_dwordx4 v[58:59], v[46:49], off offset:256
	s_mov_b64 s[54:55], 0x48000
	v_lshl_add_u64 v[94:95], v[94:95], 0, v[124:125]
	v_add_co_u32_e32 v48, vcc, s47, v122
	v_cvt_pk_bf16_f32 v78, v78, v79
	v_cvt_pk_bf16_f32 v79, v80, v81
	v_cvt_pk_bf16_f32 v80, v74, v75
	v_cvt_pk_bf16_f32 v81, v76, v77
	v_lshl_add_u64 v[46:47], v[122:123], 0, s[54:55]
	v_addc_co_u32_e32 v49, vcc, 0, v123, vcc
	v_cvt_pk_bf16_f32 v30, v30, v31
	v_cvt_pk_bf16_f32 v31, v32, v33
	v_cvt_pk_bf16_f32 v32, v26, v27
	v_cvt_pk_bf16_f32 v33, v28, v29
	s_mov_b32 s47, 0x50000
	global_store_dwordx4 v[94:95], v[78:81], off offset:256
	global_store_dwordx4 v[46:47], v[30:33], off offset:256
	s_mov_b64 s[54:55], 0x50000
	v_or_b32_e32 v78, 48, v146
	v_add_co_u32_e32 v32, vcc, s47, v122
	v_ashrrev_i32_e32 v79, 31, v78
	v_lshl_add_u64 v[30:31], v[122:123], 0, s[54:55]
	v_addc_co_u32_e32 v33, vcc, 0, v123, vcc
	v_cvt_pk_bf16_f32 v14, v14, v15
	v_cvt_pk_bf16_f32 v15, v16, v17
	v_cvt_pk_bf16_f32 v16, v10, v11
	v_cvt_pk_bf16_f32 v17, v12, v13
	s_mov_b32 s47, 0x58000
	v_lshlrev_b64 v[78:79], 11, v[78:79]
	global_store_dwordx4 v[30:31], v[14:17], off offset:256
	v_lshl_add_u64 v[78:79], s[42:43], 0, v[78:79]
	s_mov_b64 s[54:55], 0x58000
	v_add_co_u32_e32 v16, vcc, s47, v122
	v_cvt_pk_bf16_f32 v106, v118, v119
	s_nop 0
	v_addc_co_u32_e32 v17, vcc, 0, v123, vcc
	v_cvt_pk_bf16_f32 v107, v120, v121
	v_cvt_pk_bf16_f32 v108, v114, v115
	v_cvt_pk_bf16_f32 v109, v116, v117
	v_cvt_pk_bf16_f32 v90, v102, v103
	v_cvt_pk_bf16_f32 v91, v104, v105
	v_cvt_pk_bf16_f32 v92, v98, v99
	v_cvt_pk_bf16_f32 v93, v100, v101
	v_cvt_pk_bf16_f32 v74, v86, v87
	v_cvt_pk_bf16_f32 v75, v88, v89
	v_cvt_pk_bf16_f32 v76, v82, v83
	v_cvt_pk_bf16_f32 v77, v84, v85
	v_lshl_add_u64 v[78:79], v[78:79], 0, v[124:125]
	v_cvt_pk_bf16_f32 v70, v70, v71
	v_cvt_pk_bf16_f32 v71, v72, v73
	v_cvt_pk_bf16_f32 v72, v66, v67
	v_cvt_pk_bf16_f32 v73, v68, v69
	v_cvt_pk_bf16_f32 v42, v54, v55
	v_cvt_pk_bf16_f32 v43, v56, v57
	v_cvt_pk_bf16_f32 v44, v50, v51
	v_cvt_pk_bf16_f32 v45, v52, v53
	v_cvt_pk_bf16_f32 v26, v38, v39
	v_cvt_pk_bf16_f32 v27, v40, v41
	v_cvt_pk_bf16_f32 v28, v34, v35
	v_cvt_pk_bf16_f32 v29, v36, v37
	v_cvt_pk_bf16_f32 v10, v22, v23
	v_cvt_pk_bf16_f32 v11, v24, v25
	v_cvt_pk_bf16_f32 v12, v18, v19
	v_cvt_pk_bf16_f32 v13, v20, v21
	v_lshl_add_u64 v[14:15], v[122:123], 0, s[54:55]
	v_cvt_pk_bf16_f32 v6, v6, v7
	v_cvt_pk_bf16_f32 v7, v8, v9
	v_cvt_pk_bf16_f32 v8, v2, v3
	v_cvt_pk_bf16_f32 v9, v4, v5
	s_and_b64 vcc, exec, s[44:45]
	s_mov_b32 s75, s46
	s_mov_b32 s74, s48
	s_mov_b64 s[56:57], s[52:53]
	s_mov_b64 s[54:55], s[50:51]
	global_store_dwordx4 v[122:123], v[126:129], off
	global_store_dwordx4 v[110:111], v[106:109], off
	global_store_dwordx4 v[94:95], v[90:93], off
	global_store_dwordx4 v[78:79], v[74:77], off
	global_store_dwordx4 v[78:79], v[70:73], off offset:256
	global_store_dwordx4 v[60:61], v[62:65], off
	global_store_dwordx4 v[48:49], v[42:45], off
	global_store_dwordx4 v[32:33], v[26:29], off
	global_store_dwordx4 v[16:17], v[10:13], off
	global_store_dwordx4 v[14:15], v[6:9], off offset:256
	s_cbranch_vccz .LBB0_74
	s_waitcnt vmcnt(0)
	s_cmpk_gt_u32 s60, 0xff
	s_cbranch_scc1 .LBB0_81
	s_barrier

; #define PG8_STAGE(bufoff, gbase, voff) do { _Pragma("unroll") for (int _i = 0; _i < 2; ++_i) \
;         __builtin_amdgcn_global_load_lds((const unsigned*)((const char*)(gbase) + (voff)[_i]), (LAS unsigned*)(lds + (bufoff) + ldsw + _i * 8192), 16, 0, 0); } while (0)
; #define PG8_LDA(dst, b, h) do { _Pragma("unroll") for (int m = 0; m < 4; ++m) _Pragma("unroll") for (int k = 0; k < 2; ++k) dst[m][k] = *(const LAS bf16x8*)(lds + PG8_SA(b, h) + aoff + m * 2048 + k * 1024); } while (0)
; #define PG8_LDB(dst, b, h) do { _Pragma("unroll") for (int n = 0; n < 2; ++n) _Pragma("unroll") for (int k = 0; k < 2; ++k) dst[n][k] = *(const LAS bf16x8*)(lds + PG8_SB(b, h) + boff + n * 2048 + k * 1024); } while (0)
; #define PG8_MMA(ai, bj, At, Bt) do { __builtin_amdgcn_s_setprio(1); _Pragma("unroll") for (int m = 0; m < 4; ++m) _Pragma("unroll") for (int n = 0; n < 2; ++n) _Pragma("unroll") for (int k = 0; k < 2; ++k) \
;         acc[ai][bj][m][n] = __builtin_amdgcn_mfma_f32_16x16x32_bf16(Bt[n][k], At[m][k], acc[ai][bj][m][n], 0, 0, 0); __builtin_amdgcn_s_setprio(0); } while (0)
; #define PG8_WAIT_V(n) asm volatile("s_waitcnt vmcnt(" #n ")" ::: "memory")
; template <class Epi>
; __device__ __forceinline__ void gemm_phase(LAS unsigned char* lds, const Gemm g, const StaticOrder& S, const Epi& E) {
;     ...
;         for (int t = 0; t < nt; t += 2) {
;             const bool last = (t == nt - 2);
;             const char* a1 = cA + (size_t)(t + 1) * kstep;
;             const char* a2 = last ? nA : cA + (size_t)(t + 2) * kstep; const char* b2 = last ? nB : cB + (size_t)(t + 2) * kstep;
;             const char* a3 = a2 + kstep; const char* b3 = b2 + kstep;
;             PG8_LDB(B0, 0, 0); PG8_SCHED; PG8_LDA(At, 0, 0); PG8_STAGE(PG8_SA(1, 1), a1 + hstep, voffA);
;             PG8_WAIT_L(8); PG8_BAR; PG8_WAIT_L(0); PG8_MMA(0, 0, At, B0); PG8_BAR; PG8_SCHED;
;             PG8_LDB(B1, 0, 1); PG8_STAGE(PG8_SB(0, 0), b2, voffB);
;             PG8_BAR; PG8_WAIT_L(0); PG8_MMA(0, 1, At, B1); PG8_BAR;
;             PG8_LDA(At, 0, 1); PG8_STAGE(PG8_SA(0, 0), a2, voffA);
;             PG8_BAR; PG8_WAIT_L(0); PG8_MMA(1, 0, At, B0); PG8_BAR; PG8_SCHED;
;             PG8_STAGE(PG8_SB(0, 1), b2 + hstep, voffB);
;             PG8_WAIT_V(6); PG8_BAR; PG8_MMA(1, 1, At, B1); PG8_BAR;
;             PG8_LDB(B0, 1, 0); PG8_SCHED; PG8_LDA(At, 1, 0); PG8_STAGE(PG8_SA(0, 1), a2 + hstep, voffA);
.LBB0_90:
	s_add_u32 s48, s46, 0xfff80080
	s_addc_u32 s49, s47, -1
	s_add_i32 s74, 0, 0x10000
	s_cmp_eq_u32 s73, 28
	s_cselect_b32 s51, s41, s49
	s_cselect_b32 s50, s69, s48
	s_cselect_b32 s49, s39, s72
	s_cselect_b32 s48, s70, s71
	s_add_i32 m0, s56, 0xc000
	ds_read_b128 v[168:171], v151
	ds_read_b128 v[172:175], v151 offset:1024
	ds_read_b128 v[176:179], v151 offset:2048
	ds_read_b128 v[180:183], v151 offset:3072
	ds_read_b128 v[184:187], v151 offset:4096
	ds_read_b128 v[188:191], v151 offset:5120
	ds_read_b128 v[192:195], v151 offset:6144
	ds_read_b128 v[196:199], v151 offset:7168
	global_load_lds_dwordx4 v136, s[46:47]
	s_add_i32 m0, s56, 0xe000
	s_waitcnt lgkmcnt(8)
	global_load_lds_dwordx4 v138, s[46:47]
	s_barrier
	s_waitcnt lgkmcnt(0)
	v_mfma_f32_16x16x32_bf16 v[126:129], v[152:155], v[168:171], v[126:129]
	v_mfma_f32_16x16x32_bf16 v[122:125], v[160:163], v[168:171], v[122:125]
	v_mfma_f32_16x16x32_bf16 v[110:113], v[152:155], v[176:179], v[110:113]
	v_mfma_f32_16x16x32_bf16 v[102:105], v[160:163], v[176:179], v[102:105]
	v_mfma_f32_16x16x32_bf16 v[94:97], v[152:155], v[184:187], v[94:97]
	v_mfma_f32_16x16x32_bf16 v[86:89], v[160:163], v[184:187], v[86:89]
	v_mfma_f32_16x16x32_bf16 v[78:81], v[152:155], v[192:195], v[78:81]
	v_mfma_f32_16x16x32_bf16 v[70:73], v[160:163], v[192:195], v[70:73]
	v_mfma_f32_16x16x32_bf16 v[126:129], v[156:159], v[172:175], v[126:129]
	v_mfma_f32_16x16x32_bf16 v[122:125], v[164:167], v[172:175], v[122:125]
	v_mfma_f32_16x16x32_bf16 v[110:113], v[156:159], v[180:183], v[110:113]
	v_mfma_f32_16x16x32_bf16 v[102:105], v[164:167], v[180:183], v[102:105]
	v_mfma_f32_16x16x32_bf16 v[94:97], v[156:159], v[188:191], v[94:97]
	v_mfma_f32_16x16x32_bf16 v[86:89], v[164:167], v[188:191], v[86:89]
	v_mfma_f32_16x16x32_bf16 v[78:81], v[156:159], v[196:199], v[78:81]
	v_mfma_f32_16x16x32_bf16 v[70:73], v[164:167], v[196:199], v[70:73]
	s_barrier
	s_add_i32 s76, 0, 0x14000
	s_add_i32 s74, s74, s55
	s_mov_b32 m0, s74
	ds_read_b128 v[208:211], v200 offset:16384
	ds_read_b128 v[212:215], v200 offset:17408
	ds_read_b128 v[216:219], v200 offset:18432
	ds_read_b128 v[220:223], v200 offset:19456
	global_load_lds_dwordx4 v0, s[48:49]
	s_add_i32 m0, s74, 0x2000
	s_add_u32 s98, s48, s22
	global_load_lds_dwordx4 v130, s[48:49]
	s_addc_u32 s99, s49, s23
	s_barrier
	s_waitcnt lgkmcnt(0)
	v_mfma_f32_16x16x32_bf16 v[118:121], v[208:211], v[168:171], v[118:121]
	v_mfma_f32_16x16x32_bf16 v[114:117], v[216:219], v[168:171], v[114:117]
	v_mfma_f32_16x16x32_bf16 v[106:109], v[208:211], v[176:179], v[106:109]
	v_mfma_f32_16x16x32_bf16 v[98:101], v[216:219], v[176:179], v[98:101]
	v_mfma_f32_16x16x32_bf16 v[90:93], v[208:211], v[184:187], v[90:93]
	v_mfma_f32_16x16x32_bf16 v[82:85], v[216:219], v[184:187], v[82:85]
	v_mfma_f32_16x16x32_bf16 v[74:77], v[208:211], v[192:195], v[74:77]
	v_mfma_f32_16x16x32_bf16 v[66:69], v[216:219], v[192:195], v[66:69]
	v_mfma_f32_16x16x32_bf16 v[118:121], v[212:215], v[172:175], v[118:121]
	v_mfma_f32_16x16x32_bf16 v[114:117], v[220:223], v[172:175], v[114:117]
	v_mfma_f32_16x16x32_bf16 v[106:109], v[212:215], v[180:183], v[106:109]
	v_mfma_f32_16x16x32_bf16 v[98:101], v[220:223], v[180:183], v[98:101]
	v_mfma_f32_16x16x32_bf16 v[90:93], v[212:215], v[188:191], v[90:93]
	v_mfma_f32_16x16x32_bf16 v[82:85], v[220:223], v[188:191], v[82:85]
	v_mfma_f32_16x16x32_bf16 v[74:77], v[212:215], v[196:199], v[74:77]
	v_mfma_f32_16x16x32_bf16 v[66:69], v[220:223], v[196:199], v[66:69]
	s_barrier
	ds_read_b128 v[168:171], v151 offset:16384
	ds_read_b128 v[172:175], v151 offset:17408
	ds_read_b128 v[176:179], v151 offset:18432
	ds_read_b128 v[180:183], v151 offset:19456
	ds_read_b128 v[184:187], v151 offset:20480
	ds_read_b128 v[188:191], v151 offset:21504
	ds_read_b128 v[192:195], v151 offset:22528
	s_mov_b32 m0, s56
	s_add_u32 s100, s50, s22
	s_addc_u32 s101, s51, s23
	ds_read_b128 v[196:199], v151 offset:23552
	global_load_lds_dwordx4 v134, s[50:51]
	s_mov_b32 m0, s57
	s_waitcnt vmcnt(9)
	global_load_lds_dwordx4 v132, s[50:51]
	s_barrier
	s_waitcnt lgkmcnt(0)
	v_mfma_f32_16x16x32_bf16 v[62:65], v[152:155], v[168:171], v[62:65]
	v_mfma_f32_16x16x32_bf16 v[54:57], v[160:163], v[168:171], v[54:57]
	v_mfma_f32_16x16x32_bf16 v[46:49], v[152:155], v[176:179], v[46:49]
	v_mfma_f32_16x16x32_bf16 v[38:41], v[160:163], v[176:179], v[38:41]
	v_mfma_f32_16x16x32_bf16 v[30:33], v[152:155], v[184:187], v[30:33]
	v_mfma_f32_16x16x32_bf16 v[22:25], v[160:163], v[184:187], v[22:25]
	v_mfma_f32_16x16x32_bf16 v[14:17], v[152:155], v[192:195], v[14:17]
	v_mfma_f32_16x16x32_bf16 v[6:9], v[160:163], v[192:195], v[6:9]
	v_mfma_f32_16x16x32_bf16 v[62:65], v[156:159], v[172:175], v[62:65]
	v_mfma_f32_16x16x32_bf16 v[54:57], v[164:167], v[172:175], v[54:57]
	v_mfma_f32_16x16x32_bf16 v[46:49], v[156:159], v[180:183], v[46:49]
	v_mfma_f32_16x16x32_bf16 v[38:41], v[164:167], v[180:183], v[38:41]
	v_mfma_f32_16x16x32_bf16 v[30:33], v[156:159], v[188:191], v[30:33]
	v_mfma_f32_16x16x32_bf16 v[22:25], v[164:167], v[188:191], v[22:25]
	v_mfma_f32_16x16x32_bf16 v[14:17], v[156:159], v[196:199], v[14:17]
	v_mfma_f32_16x16x32_bf16 v[6:9], v[164:167], v[196:199], v[6:9]
	s_barrier
	ds_read_b128 v[152:155], v200 offset:32768
	ds_read_b128 v[156:159], v200 offset:33792
	ds_read_b128 v[160:163], v200 offset:34816
	ds_read_b128 v[164:167], v200 offset:35840
	s_add_i32 s76, s76, s55
	s_mov_b32 m0, s76
	s_add_u32 s74, s48, 0x80000
	s_addc_u32 s75, s49, 0
	global_load_lds_dwordx4 v0, s[74:75]
	s_add_i32 m0, s76, 0x2000
	s_waitcnt vmcnt(5)
	global_load_lds_dwordx4 v130, s[74:75]
	s_barrier
; #define PG8_STAGE(bufoff, gbase, voff) do { _Pragma("unroll") for (int _i = 0; _i < 2; ++_i) \
;         __builtin_amdgcn_global_load_lds((const unsigned*)((const char*)(gbase) + (voff)[_i]), (LAS unsigned*)(lds + (bufoff) + ldsw + _i * 8192), 16, 0, 0); } while (0)
; #define PG8_LDA(dst, b, h) do { _Pragma("unroll") for (int m = 0; m < 4; ++m) _Pragma("unroll") for (int k = 0; k < 2; ++k) dst[m][k] = *(const LAS bf16x8*)(lds + PG8_SA(b, h) + aoff + m * 2048 + k * 1024); } while (0)
; #define PG8_LDB(dst, b, h) do { _Pragma("unroll") for (int n = 0; n < 2; ++n) _Pragma("unroll") for (int k = 0; k < 2; ++k) dst[n][k] = *(const LAS bf16x8*)(lds + PG8_SB(b, h) + boff + n * 2048 + k * 1024); } while (0)
; #define PG8_MMA(ai, bj, At, Bt) do { __builtin_amdgcn_s_setprio(1); _Pragma("unroll") for (int m = 0; m < 4; ++m) _Pragma("unroll") for (int n = 0; n < 2; ++n) _Pragma("unroll") for (int k = 0; k < 2; ++k) \
;         acc[ai][bj][m][n] = __builtin_amdgcn_mfma_f32_16x16x32_bf16(Bt[n][k], At[m][k], acc[ai][bj][m][n], 0, 0, 0); __builtin_amdgcn_s_setprio(0); } while (0)
; #define PG8_WAIT_V(n) asm volatile("s_waitcnt vmcnt(" #n ")" ::: "memory")
; #define PG8_WAIT_L(n) asm volatile("s_waitcnt lgkmcnt(" #n ")" ::: "memory")
; #define PG8_BAR __builtin_amdgcn_s_barrier()
; #define PG8_SCHED __builtin_amdgcn_sched_barrier(0)
; template <class Epi>
; __device__ __forceinline__ void gemm_phase(LAS unsigned char* lds, const Gemm g, const StaticOrder& S, const Epi& E) {
;     ...
;             PG8_LDB(B0, 1, 0); PG8_SCHED; PG8_LDA(At, 1, 0); PG8_STAGE(PG8_SA(0, 1), a2 + hstep, voffA);
;             PG8_WAIT_L(8); PG8_BAR; PG8_WAIT_L(0); PG8_MMA(0, 0, At, B0); PG8_BAR; PG8_SCHED;
;             PG8_LDB(B1, 1, 1); PG8_STAGE(PG8_SB(1, 0), b3, voffB);
;             PG8_BAR; PG8_WAIT_L(0); PG8_MMA(0, 1, At, B1); PG8_BAR;
;             PG8_LDA(At, 1, 1); PG8_STAGE(PG8_SA(1, 0), a3, voffA);
;             PG8_BAR; PG8_WAIT_L(0); PG8_MMA(1, 0, At, B0); PG8_BAR; PG8_SCHED;
;             PG8_STAGE(PG8_SB(1, 1), b3 + hstep, voffB);
;             PG8_WAIT_V(6); PG8_BAR; PG8_MMA(1, 1, At, B1); PG8_BAR;
	v_mfma_f32_16x16x32_bf16 v[58:61], v[208:211], v[168:171], v[58:61]
	v_mfma_f32_16x16x32_bf16 v[50:53], v[216:219], v[168:171], v[50:53]
	v_mfma_f32_16x16x32_bf16 v[42:45], v[208:211], v[176:179], v[42:45]
	v_mfma_f32_16x16x32_bf16 v[34:37], v[216:219], v[176:179], v[34:37]
	v_mfma_f32_16x16x32_bf16 v[26:29], v[208:211], v[184:187], v[26:29]
	v_mfma_f32_16x16x32_bf16 v[18:21], v[216:219], v[184:187], v[18:21]
	v_mfma_f32_16x16x32_bf16 v[10:13], v[208:211], v[192:195], v[10:13]
	v_mfma_f32_16x16x32_bf16 v[2:5], v[216:219], v[192:195], v[2:5]
	v_mfma_f32_16x16x32_bf16 v[58:61], v[212:215], v[172:175], v[58:61]
	v_mfma_f32_16x16x32_bf16 v[50:53], v[220:223], v[172:175], v[50:53]
	v_mfma_f32_16x16x32_bf16 v[42:45], v[212:215], v[180:183], v[42:45]
	v_mfma_f32_16x16x32_bf16 v[34:37], v[220:223], v[180:183], v[34:37]
	v_mfma_f32_16x16x32_bf16 v[26:29], v[212:215], v[188:191], v[26:29]
	v_mfma_f32_16x16x32_bf16 v[18:21], v[220:223], v[188:191], v[18:21]
	v_mfma_f32_16x16x32_bf16 v[10:13], v[212:215], v[196:199], v[10:13]
	v_mfma_f32_16x16x32_bf16 v[2:5], v[220:223], v[196:199], v[2:5]
	s_barrier
	s_add_u32 s50, s50, 0x80000
	s_addc_u32 s51, s51, 0
	s_mov_b32 m0, s58
	ds_read_b128 v[168:171], v151 offset:32768
	ds_read_b128 v[172:175], v151 offset:33792
	ds_read_b128 v[176:179], v151 offset:34816
	ds_read_b128 v[180:183], v151 offset:35840
	ds_read_b128 v[184:187], v151 offset:36864
	ds_read_b128 v[188:191], v151 offset:37888
	ds_read_b128 v[192:195], v151 offset:38912
	s_add_i32 s74, 0, 0x18000
	ds_read_b128 v[196:199], v151 offset:39936
	global_load_lds_dwordx4 v134, s[50:51]
	s_mov_b32 m0, s59
	s_waitcnt lgkmcnt(8)
	global_load_lds_dwordx4 v132, s[50:51]
	s_barrier
	s_waitcnt lgkmcnt(0)
	v_mfma_f32_16x16x32_bf16 v[126:129], v[152:155], v[168:171], v[126:129]
	v_mfma_f32_16x16x32_bf16 v[122:125], v[160:163], v[168:171], v[122:125]
	v_mfma_f32_16x16x32_bf16 v[110:113], v[152:155], v[176:179], v[110:113]
	v_mfma_f32_16x16x32_bf16 v[102:105], v[160:163], v[176:179], v[102:105]
	v_mfma_f32_16x16x32_bf16 v[94:97], v[152:155], v[184:187], v[94:97]
	v_mfma_f32_16x16x32_bf16 v[86:89], v[160:163], v[184:187], v[86:89]
	v_mfma_f32_16x16x32_bf16 v[78:81], v[152:155], v[192:195], v[78:81]
	v_mfma_f32_16x16x32_bf16 v[70:73], v[160:163], v[192:195], v[70:73]
	v_mfma_f32_16x16x32_bf16 v[126:129], v[156:159], v[172:175], v[126:129]
	v_mfma_f32_16x16x32_bf16 v[122:125], v[164:167], v[172:175], v[122:125]
	v_mfma_f32_16x16x32_bf16 v[110:113], v[156:159], v[180:183], v[110:113]
	v_mfma_f32_16x16x32_bf16 v[102:105], v[164:167], v[180:183], v[102:105]
	v_mfma_f32_16x16x32_bf16 v[94:97], v[156:159], v[188:191], v[94:97]
	v_mfma_f32_16x16x32_bf16 v[86:89], v[164:167], v[188:191], v[86:89]
	v_mfma_f32_16x16x32_bf16 v[78:81], v[156:159], v[196:199], v[78:81]
	v_mfma_f32_16x16x32_bf16 v[70:73], v[164:167], v[196:199], v[70:73]
	s_barrier
	s_add_i32 s51, s74, s55
	s_mov_b32 m0, s51
	ds_read_b128 v[208:211], v200 offset:49152
	ds_read_b128 v[212:215], v200 offset:50176
	ds_read_b128 v[216:219], v200 offset:51200
	ds_read_b128 v[220:223], v200 offset:52224
	global_load_lds_dwordx4 v0, s[98:99]
	s_add_i32 m0, s51, 0x2000
	s_add_i32 s50, 0, 0x1c000
	global_load_lds_dwordx4 v130, s[98:99]
	s_barrier
	s_waitcnt lgkmcnt(0)
	v_mfma_f32_16x16x32_bf16 v[118:121], v[208:211], v[168:171], v[118:121]
	v_mfma_f32_16x16x32_bf16 v[114:117], v[216:219], v[168:171], v[114:117]
	v_mfma_f32_16x16x32_bf16 v[106:109], v[208:211], v[176:179], v[106:109]
	v_mfma_f32_16x16x32_bf16 v[98:101], v[216:219], v[176:179], v[98:101]
	v_mfma_f32_16x16x32_bf16 v[90:93], v[208:211], v[184:187], v[90:93]
	v_mfma_f32_16x16x32_bf16 v[82:85], v[216:219], v[184:187], v[82:85]
	v_mfma_f32_16x16x32_bf16 v[74:77], v[208:211], v[192:195], v[74:77]
	v_mfma_f32_16x16x32_bf16 v[66:69], v[216:219], v[192:195], v[66:69]
	v_mfma_f32_16x16x32_bf16 v[118:121], v[212:215], v[172:175], v[118:121]
	v_mfma_f32_16x16x32_bf16 v[114:117], v[220:223], v[172:175], v[114:117]
	v_mfma_f32_16x16x32_bf16 v[106:109], v[212:215], v[180:183], v[106:109]
	v_mfma_f32_16x16x32_bf16 v[98:101], v[220:223], v[180:183], v[98:101]
	v_mfma_f32_16x16x32_bf16 v[90:93], v[212:215], v[188:191], v[90:93]
	v_mfma_f32_16x16x32_bf16 v[82:85], v[220:223], v[188:191], v[82:85]
	v_mfma_f32_16x16x32_bf16 v[74:77], v[212:215], v[196:199], v[74:77]
	v_mfma_f32_16x16x32_bf16 v[66:69], v[220:223], v[196:199], v[66:69]
	s_barrier
	ds_read_b128 v[168:171], v151 offset:49152
	ds_read_b128 v[172:175], v151 offset:50176
	ds_read_b128 v[176:179], v151 offset:51200
	ds_read_b128 v[180:183], v151 offset:52224
	ds_read_b128 v[184:187], v151 offset:53248
	ds_read_b128 v[188:191], v151 offset:54272
	ds_read_b128 v[192:195], v151 offset:55296
	s_mov_b32 m0, s61
	ds_read_b128 v[196:199], v151 offset:56320
	global_load_lds_dwordx4 v134, s[100:101]
	s_mov_b32 m0, s63
	s_waitcnt vmcnt(9)
	global_load_lds_dwordx4 v132, s[100:101]
	s_barrier
	s_waitcnt lgkmcnt(0)
	v_mfma_f32_16x16x32_bf16 v[62:65], v[152:155], v[168:171], v[62:65]
	v_mfma_f32_16x16x32_bf16 v[54:57], v[160:163], v[168:171], v[54:57]
	v_mfma_f32_16x16x32_bf16 v[46:49], v[152:155], v[176:179], v[46:49]
	v_mfma_f32_16x16x32_bf16 v[38:41], v[160:163], v[176:179], v[38:41]
	v_mfma_f32_16x16x32_bf16 v[30:33], v[152:155], v[184:187], v[30:33]
	v_mfma_f32_16x16x32_bf16 v[22:25], v[160:163], v[184:187], v[22:25]
	v_mfma_f32_16x16x32_bf16 v[14:17], v[152:155], v[192:195], v[14:17]
	v_mfma_f32_16x16x32_bf16 v[6:9], v[160:163], v[192:195], v[6:9]
	v_mfma_f32_16x16x32_bf16 v[62:65], v[156:159], v[172:175], v[62:65]
	v_mfma_f32_16x16x32_bf16 v[54:57], v[164:167], v[172:175], v[54:57]
	v_mfma_f32_16x16x32_bf16 v[46:49], v[156:159], v[180:183], v[46:49]
	v_mfma_f32_16x16x32_bf16 v[38:41], v[164:167], v[180:183], v[38:41]
	v_mfma_f32_16x16x32_bf16 v[30:33], v[156:159], v[188:191], v[30:33]
	v_mfma_f32_16x16x32_bf16 v[22:25], v[164:167], v[188:191], v[22:25]
	v_mfma_f32_16x16x32_bf16 v[14:17], v[156:159], v[196:199], v[14:17]
	v_mfma_f32_16x16x32_bf16 v[6:9], v[164:167], v[196:199], v[6:9]
	s_barrier
; __device__ __forceinline__ unsigned pk2(float lo, float hi) { f32x2 v = {lo, hi}; bf16x2_t b = __builtin_convertvector(v, bf16x2_t); return __builtin_bit_cast(unsigned, b); }
; #define PG8_MMA(ai, bj, At, Bt) do { __builtin_amdgcn_s_setprio(1); _Pragma("unroll") for (int m = 0; m < 4; ++m) _Pragma("unroll") for (int n = 0; n < 2; ++n) _Pragma("unroll") for (int k = 0; k < 2; ++k) \
;         acc[ai][bj][m][n] = __builtin_amdgcn_mfma_f32_16x16x32_bf16(Bt[n][k], At[m][k], acc[ai][bj][m][n], 0, 0, 0); __builtin_amdgcn_s_setprio(0); } while (0)
; #define PG8_BAR __builtin_amdgcn_s_barrier()
;     __device__ __forceinline__ void operator()(const AccT& acc, const Unit& u, int wr, int wc, int fr, int fq) const {
;         const int row0 = u.pm * BM + wr * 64 + fr, col0 = u.pn * 128 + wc * 32 + 8 * fq;
;         float rsv[8];
;         {
;             const int ln = (fq << 4) | fr;
;             float sa = ss[u.pm * BM + wr * 64 + ln], sb = ss[u.pm * BM + HALF + wr * 64 + ln];
;             sa = __builtin_amdgcn_rsqf(sa * (1.0f / DM) + EPS); sb = __builtin_amdgcn_rsqf(sb * (1.0f / DM) + EPS);
; #pragma unroll
;             for (int m = 0; m < 4; ++m) { rsv[m] = __shfl(sa, 16 * m + fr); rsv[4 + m] = __shfl(sb, 16 * m + fr); }
;         }
; #pragma unroll
;         for (int ai = 0; ai < 2; ++ai)
; #pragma unroll
;             for (int m = 0; m < 4; ++m) {
;                 const int row = row0 + ai * HALF + m * 16;
;                 const float rs = rsv[ai * 4 + m];
;                 float v[8];
; #pragma unroll
;                 for (int n = 0; n < 2; ++n)
; #pragma unroll
;                     for (int j = 0; j < 4; ++j) {
;                         const float g = acc[ai][0][m][n][j] * rs, up = acc[ai][1][m][n][j] * rs;
;                         const float sg = __builtin_amdgcn_rcpf(1.0f + __builtin_amdgcn_exp2f(-g * LOG2E));
;                         v[4 * n + j] = g * sg * up;
;                     }
;                 u32x4 w; w.x = pk2(v[0], v[1]); w.y = pk2(v[2], v[3]); w.z = pk2(v[4], v[5]); w.w = pk2(v[6], v[7]);
;                 *(u32x4*)(mid + (size_t)row * FF + col0) = w;
; template <class Epi>
; __device__ __forceinline__ void gemm_phase(LAS unsigned char* lds, const Gemm g, const StaticOrder& S, const Epi& E) {
;     ...
;             PG8_WAIT_V(6); PG8_BAR; PG8_MMA(1, 1, At, B1); PG8_BAR;
;         }
;         E(acc, cur, wr, wc, fr, fq);
	ds_read_b128 v[152:155], v200
	ds_read_b128 v[156:159], v200 offset:1024
	ds_read_b128 v[160:163], v200 offset:2048
	s_add_i32 s73, s73, 2
	s_add_u32 s46, s46, 0x100
	s_addc_u32 s47, s47, 0
	s_add_u32 s71, s71, 0x100
	s_addc_u32 s72, s72, 0
	ds_read_b128 v[164:167], v200 offset:3072
	s_add_i32 s50, s50, s55
	s_mov_b32 m0, s50
	s_add_u32 s48, s48, 0x80080
	s_addc_u32 s49, s49, 0
	global_load_lds_dwordx4 v0, s[48:49]
	s_add_i32 m0, s50, 0x2000
	s_waitcnt vmcnt(5)
	global_load_lds_dwordx4 v130, s[48:49]
	s_barrier
	v_mfma_f32_16x16x32_bf16 v[58:61], v[208:211], v[168:171], v[58:61]
	v_mfma_f32_16x16x32_bf16 v[50:53], v[216:219], v[168:171], v[50:53]
	v_mfma_f32_16x16x32_bf16 v[42:45], v[208:211], v[176:179], v[42:45]
	v_mfma_f32_16x16x32_bf16 v[34:37], v[216:219], v[176:179], v[34:37]
	v_mfma_f32_16x16x32_bf16 v[26:29], v[208:211], v[184:187], v[26:29]
	v_mfma_f32_16x16x32_bf16 v[18:21], v[216:219], v[184:187], v[18:21]
	v_mfma_f32_16x16x32_bf16 v[10:13], v[208:211], v[192:195], v[10:13]
	v_mfma_f32_16x16x32_bf16 v[2:5], v[216:219], v[192:195], v[2:5]
	v_mfma_f32_16x16x32_bf16 v[58:61], v[212:215], v[172:175], v[58:61]
	v_mfma_f32_16x16x32_bf16 v[50:53], v[220:223], v[172:175], v[50:53]
	v_mfma_f32_16x16x32_bf16 v[42:45], v[212:215], v[180:183], v[42:45]
	v_mfma_f32_16x16x32_bf16 v[34:37], v[220:223], v[180:183], v[34:37]
	v_mfma_f32_16x16x32_bf16 v[26:29], v[212:215], v[188:191], v[26:29]
	v_mfma_f32_16x16x32_bf16 v[18:21], v[220:223], v[188:191], v[18:21]
	v_mfma_f32_16x16x32_bf16 v[10:13], v[212:215], v[196:199], v[10:13]
	v_mfma_f32_16x16x32_bf16 v[2:5], v[220:223], v[196:199], v[2:5]
	s_cmp_gt_u32 s73, 29
	s_barrier
	s_cbranch_scc0 .LBB0_90
	s_waitcnt lgkmcnt(0)
	s_lshl_b32 s39, s68, 8
	s_add_i32 s39, s39, s60
	v_or_b32_e32 v154, s39, v145
	v_ashrrev_i32_e32 v155, 31, v154
	v_lshl_add_u64 v[154:155], v[154:155], 2, s[2:3]
	global_load_dword v140, v[154:155], off
	v_add_u32_e32 v154, s39, v147
	v_ashrrev_i32_e32 v155, 31, v154
	v_lshl_add_u64 v[154:155], v[154:155], 2, s[2:3]
	global_load_dword v142, v[154:155], off
	v_readlane_b32 s46, v251, 58
	v_readlane_b32 s47, v251, 59
	v_or_b32_e32 v153, s39, v141
	s_movk_i32 s39, 0x2c00
	s_and_b64 vcc, exec, s[36:37]
	s_mov_b32 s68, s40
	s_mov_b64 s[48:49], s[44:45]
	s_waitcnt vmcnt(0)
	v_fmamk_f32 v140, v140, 0x3a000000, v233
	v_rsq_f32_e32 v140, v140
	v_fmamk_f32 v142, v142, 0x3a000000, v233
	v_rsq_f32_e32 v154, v142
	v_and_or_b32 v142, v234, 64, v141
	v_lshlrev_b32_e32 v155, 2, v142
	ds_bpermute_b32 v156, v155, v140
	ds_bpermute_b32 v152, v155, v140 offset:64
	ds_bpermute_b32 v146, v155, v154
	ds_bpermute_b32 v144, v155, v154 offset:64
	ds_bpermute_b32 v150, v155, v140 offset:128
	s_waitcnt lgkmcnt(0)
	v_pk_mul_f32 v[126:127], v[126:127], v[156:157] op_sel_hi:[1,0]
	ds_bpermute_b32 v142, v155, v154 offset:128
	v_mul_f32_e32 v157, 0xbfb8aa3b, v126
	v_exp_f32_e32 v157, v157
	ds_bpermute_b32 v148, v155, v140 offset:192
	ds_bpermute_b32 v140, v155, v154 offset:192
	v_lshl_or_b32 v154, s65, 7, v149
	v_add_f32_e32 v157, 1.0, v157
	v_rcp_f32_e32 v158, v157
	v_pk_mul_f32 v[118:119], v[118:119], v[156:157] op_sel_hi:[1,0]
	v_mul_f32_e32 v157, 0xbfb8aa3b, v127
	v_exp_f32_e32 v157, v157
	v_ashrrev_i32_e32 v155, 31, v154
	v_pk_mul_f32 v[110:111], v[110:111], v[152:153] op_sel_hi:[1,0]
	v_pk_mul_f32 v[106:107], v[106:107], v[152:153] op_sel_hi:[1,0]
	v_add_f32_e32 v157, 1.0, v157
	v_rcp_f32_e32 v159, v157
	v_pk_mul_f32 v[120:121], v[120:121], v[156:157] op_sel_hi:[1,0]
	v_pk_mul_f32 v[122:123], v[122:123], v[156:157] op_sel_hi:[1,0]
	v_pk_mul_f32 v[114:115], v[114:115], v[156:157] op_sel_hi:[1,0]
	v_pk_mul_f32 v[126:127], v[126:127], v[158:159]
	v_pk_mul_f32 v[116:117], v[116:117], v[156:157] op_sel_hi:[1,0]
	v_pk_mul_f32 v[118:119], v[118:119], v[126:127]
	v_pk_mul_f32 v[126:127], v[128:129], v[156:157] op_sel_hi:[1,0]
	v_pk_mul_f32 v[108:109], v[108:109], v[152:153] op_sel_hi:[1,0]
	v_mul_f32_e32 v128, 0xbfb8aa3b, v126
	v_mul_f32_e32 v129, 0xbfb8aa3b, v127
	v_exp_f32_e32 v128, v128
	v_exp_f32_e32 v129, v129
	v_pk_mul_f32 v[102:103], v[102:103], v[152:153] op_sel_hi:[1,0]
	v_pk_mul_f32 v[98:99], v[98:99], v[152:153] op_sel_hi:[1,0]
	v_add_f32_e32 v128, 1.0, v128
	v_add_f32_e32 v129, 1.0, v129
	v_rcp_f32_e32 v128, v128
	v_rcp_f32_e32 v129, v129
	v_pk_mul_f32 v[100:101], v[100:101], v[152:153] op_sel_hi:[1,0]
	v_pk_mul_f32 v[94:95], v[94:95], v[150:151] op_sel_hi:[1,0]
	v_pk_mul_f32 v[90:91], v[90:91], v[150:151] op_sel_hi:[1,0]
	v_pk_mul_f32 v[126:127], v[126:127], v[128:129]
	v_pk_mul_f32 v[92:93], v[92:93], v[150:151] op_sel_hi:[1,0]
	v_pk_mul_f32 v[120:121], v[120:121], v[126:127]
	v_mul_f32_e32 v126, 0xbfb8aa3b, v122
	v_mul_f32_e32 v127, 0xbfb8aa3b, v123
	v_exp_f32_e32 v126, v126
	v_exp_f32_e32 v127, v127
	v_pk_mul_f32 v[86:87], v[86:87], v[150:151] op_sel_hi:[1,0]
	v_pk_mul_f32 v[82:83], v[82:83], v[150:151] op_sel_hi:[1,0]
	v_add_f32_e32 v126, 1.0, v126
	v_add_f32_e32 v127, 1.0, v127
	v_rcp_f32_e32 v126, v126
	v_rcp_f32_e32 v127, v127
	v_pk_mul_f32 v[84:85], v[84:85], v[150:151] op_sel_hi:[1,0]
	s_waitcnt lgkmcnt(1)
; __device__ __forceinline__ unsigned pk2(float lo, float hi) { f32x2 v = {lo, hi}; bf16x2_t b = __builtin_convertvector(v, bf16x2_t); return __builtin_bit_cast(unsigned, b); }
;     __device__ __forceinline__ void operator()(const AccT& acc, const Unit& u, int wr, int wc, int fr, int fq) const {
;     ...
; #pragma unroll
;         for (int ai = 0; ai < 2; ++ai)
; #pragma unroll
;             for (int m = 0; m < 4; ++m) {
;                 const int row = row0 + ai * HALF + m * 16;
;                 const float rs = rsv[ai * 4 + m];
;                 float v[8];
; #pragma unroll
;                 for (int n = 0; n < 2; ++n)
; #pragma unroll
;                     for (int j = 0; j < 4; ++j) {
;                         const float g = acc[ai][0][m][n][j] * rs, up = acc[ai][1][m][n][j] * rs;
;                         const float sg = __builtin_amdgcn_rcpf(1.0f + __builtin_amdgcn_exp2f(-g * LOG2E));
;                         v[4 * n + j] = g * sg * up;
;                     }
;                 u32x4 w; w.x = pk2(v[0], v[1]); w.y = pk2(v[2], v[3]); w.z = pk2(v[4], v[5]); w.w = pk2(v[6], v[7]);
;                 *(u32x4*)(mid + (size_t)row * FF + col0) = w;
;             }
	v_pk_mul_f32 v[78:79], v[78:79], v[148:149] op_sel_hi:[1,0]
	v_pk_mul_f32 v[74:75], v[74:75], v[148:149] op_sel_hi:[1,0]
	v_pk_mul_f32 v[122:123], v[122:123], v[126:127]
	v_pk_mul_f32 v[76:77], v[76:77], v[148:149] op_sel_hi:[1,0]
	v_pk_mul_f32 v[122:123], v[114:115], v[122:123]
	v_pk_mul_f32 v[114:115], v[124:125], v[156:157] op_sel_hi:[1,0]
	v_pk_mul_f32 v[70:71], v[70:71], v[148:149] op_sel_hi:[1,0]
	v_mul_f32_e32 v124, 0xbfb8aa3b, v114
	v_mul_f32_e32 v125, 0xbfb8aa3b, v115
	v_exp_f32_e32 v124, v124
	v_exp_f32_e32 v125, v125
	v_pk_mul_f32 v[66:67], v[66:67], v[148:149] op_sel_hi:[1,0]
	v_pk_mul_f32 v[68:69], v[68:69], v[148:149] op_sel_hi:[1,0]
	v_add_f32_e32 v124, 1.0, v124
	v_add_f32_e32 v125, 1.0, v125
	v_rcp_f32_e32 v124, v124
	v_rcp_f32_e32 v125, v125
	v_pk_mul_f32 v[62:63], v[62:63], v[146:147] op_sel_hi:[1,0]
	v_pk_mul_f32 v[58:59], v[58:59], v[146:147] op_sel_hi:[1,0]
	v_pk_mul_f32 v[60:61], v[60:61], v[146:147] op_sel_hi:[1,0]
	v_pk_mul_f32 v[114:115], v[114:115], v[124:125]
	v_pk_mul_f32 v[54:55], v[54:55], v[146:147] op_sel_hi:[1,0]
	v_pk_mul_f32 v[124:125], v[116:117], v[114:115]
	v_cvt_pk_bf16_f32 v114, v118, v119
	v_mov_b64_e32 v[118:119], s[46:47]
	v_cvt_pk_bf16_f32 v115, v120, v121
	v_cvt_pk_bf16_f32 v116, v122, v123
	v_mad_i64_i32 v[122:123], s[46:47], v153, s39, v[118:119]
	v_lshlrev_b64 v[120:121], 1, v[154:155]
	v_cvt_pk_bf16_f32 v117, v124, v125
	v_lshl_add_u64 v[122:123], v[122:123], 0, v[120:121]
	global_store_dwordx4 v[122:123], v[114:117], off
	v_pk_mul_f32 v[50:51], v[50:51], v[146:147] op_sel_hi:[1,0]
	v_pk_mul_f32 v[52:53], v[52:53], v[146:147] op_sel_hi:[1,0]
	v_mul_f32_e32 v114, 0xbfb8aa3b, v110
	v_mul_f32_e32 v115, 0xbfb8aa3b, v111
	v_exp_f32_e32 v114, v114
	v_exp_f32_e32 v115, v115
	v_pk_mul_f32 v[46:47], v[46:47], v[144:145] op_sel_hi:[1,0]
	v_pk_mul_f32 v[42:43], v[42:43], v[144:145] op_sel_hi:[1,0]
	v_add_f32_e32 v114, 1.0, v114
	v_add_f32_e32 v115, 1.0, v115
	v_rcp_f32_e32 v114, v114
	v_rcp_f32_e32 v115, v115
	v_pk_mul_f32 v[44:45], v[44:45], v[144:145] op_sel_hi:[1,0]
	v_pk_mul_f32 v[38:39], v[38:39], v[144:145] op_sel_hi:[1,0]
	v_pk_mul_f32 v[34:35], v[34:35], v[144:145] op_sel_hi:[1,0]
	v_pk_mul_f32 v[110:111], v[110:111], v[114:115]
	v_pk_mul_f32 v[36:37], v[36:37], v[144:145] op_sel_hi:[1,0]
	v_pk_mul_f32 v[106:107], v[106:107], v[110:111]
	v_pk_mul_f32 v[110:111], v[112:113], v[152:153] op_sel_hi:[1,0]
	v_pk_mul_f32 v[30:31], v[30:31], v[142:143] op_sel_hi:[1,0]
	v_mul_f32_e32 v112, 0xbfb8aa3b, v110
	v_mul_f32_e32 v113, 0xbfb8aa3b, v111
	v_exp_f32_e32 v112, v112
	v_exp_f32_e32 v113, v113
	v_pk_mul_f32 v[26:27], v[26:27], v[142:143] op_sel_hi:[1,0]
	v_pk_mul_f32 v[28:29], v[28:29], v[142:143] op_sel_hi:[1,0]
	v_add_f32_e32 v112, 1.0, v112
	v_add_f32_e32 v113, 1.0, v113
	v_rcp_f32_e32 v112, v112
	v_rcp_f32_e32 v113, v113
	v_pk_mul_f32 v[22:23], v[22:23], v[142:143] op_sel_hi:[1,0]
	v_pk_mul_f32 v[18:19], v[18:19], v[142:143] op_sel_hi:[1,0]
	v_pk_mul_f32 v[20:21], v[20:21], v[142:143] op_sel_hi:[1,0]
	v_pk_mul_f32 v[110:111], v[110:111], v[112:113]
	s_waitcnt lgkmcnt(0)
	v_pk_mul_f32 v[14:15], v[14:15], v[140:141] op_sel_hi:[1,0]
	v_pk_mul_f32 v[108:109], v[108:109], v[110:111]
	v_mul_f32_e32 v110, 0xbfb8aa3b, v102
	v_mul_f32_e32 v111, 0xbfb8aa3b, v103
	v_exp_f32_e32 v110, v110
	v_exp_f32_e32 v111, v111
	v_pk_mul_f32 v[10:11], v[10:11], v[140:141] op_sel_hi:[1,0]
	v_pk_mul_f32 v[12:13], v[12:13], v[140:141] op_sel_hi:[1,0]
	v_add_f32_e32 v110, 1.0, v110
	v_add_f32_e32 v111, 1.0, v111
	v_rcp_f32_e32 v110, v110
	v_rcp_f32_e32 v111, v111
	v_pk_mul_f32 v[6:7], v[6:7], v[140:141] op_sel_hi:[1,0]
	v_pk_mul_f32 v[2:3], v[2:3], v[140:141] op_sel_hi:[1,0]
	v_pk_mul_f32 v[4:5], v[4:5], v[140:141] op_sel_hi:[1,0]
	v_pk_mul_f32 v[102:103], v[102:103], v[110:111]
	v_or_b32_e32 v110, 16, v153
	v_pk_mul_f32 v[102:103], v[98:99], v[102:103]
	v_pk_mul_f32 v[98:99], v[104:105], v[152:153] op_sel_hi:[1,0]
	s_mov_b32 s65, s38
	v_mul_f32_e32 v104, 0xbfb8aa3b, v98
	v_mul_f32_e32 v105, 0xbfb8aa3b, v99
	v_exp_f32_e32 v104, v104
	v_exp_f32_e32 v105, v105
	v_add_f32_e32 v104, 1.0, v104
	v_add_f32_e32 v105, 1.0, v105
	v_rcp_f32_e32 v104, v104
	v_rcp_f32_e32 v105, v105
	s_nop 0
	v_pk_mul_f32 v[98:99], v[98:99], v[104:105]
	s_nop 0
	v_pk_mul_f32 v[104:105], v[100:101], v[98:99]
	v_cvt_pk_bf16_f32 v100, v102, v103
	v_mad_i64_i32 v[102:103], s[46:47], v110, s39, v[118:119]
	v_cvt_pk_bf16_f32 v98, v106, v107
	v_cvt_pk_bf16_f32 v99, v108, v109
	v_cvt_pk_bf16_f32 v101, v104, v105
	v_lshl_add_u64 v[102:103], v[102:103], 0, v[120:121]
	global_store_dwordx4 v[102:103], v[98:101], off
	s_nop 1
	v_mul_f32_e32 v98, 0xbfb8aa3b, v94
	v_mul_f32_e32 v99, 0xbfb8aa3b, v95
	v_exp_f32_e32 v98, v98
	v_exp_f32_e32 v99, v99
	v_add_f32_e32 v98, 1.0, v98
	v_add_f32_e32 v99, 1.0, v99
	v_rcp_f32_e32 v98, v98
	v_rcp_f32_e32 v99, v99
	s_nop 0
	v_pk_mul_f32 v[94:95], v[94:95], v[98:99]
	s_nop 0
	v_pk_mul_f32 v[90:91], v[90:91], v[94:95]
	v_pk_mul_f32 v[94:95], v[96:97], v[150:151] op_sel_hi:[1,0]
	s_nop 0
	v_mul_f32_e32 v96, 0xbfb8aa3b, v94
	v_mul_f32_e32 v97, 0xbfb8aa3b, v95
	v_exp_f32_e32 v96, v96
	v_exp_f32_e32 v97, v97
	v_add_f32_e32 v96, 1.0, v96
	v_add_f32_e32 v97, 1.0, v97
	v_rcp_f32_e32 v96, v96
	v_rcp_f32_e32 v97, v97
	s_nop 0
	v_pk_mul_f32 v[94:95], v[94:95], v[96:97]
	s_nop 0
	v_pk_mul_f32 v[92:93], v[92:93], v[94:95]
	v_mul_f32_e32 v94, 0xbfb8aa3b, v86
	v_mul_f32_e32 v95, 0xbfb8aa3b, v87
	v_exp_f32_e32 v94, v94
	v_exp_f32_e32 v95, v95
	v_add_f32_e32 v94, 1.0, v94
	v_add_f32_e32 v95, 1.0, v95
	v_rcp_f32_e32 v94, v94
	v_rcp_f32_e32 v95, v95
	s_nop 0
	v_pk_mul_f32 v[86:87], v[86:87], v[94:95]
	s_nop 0
	v_pk_mul_f32 v[86:87], v[82:83], v[86:87]
; __device__ __forceinline__ unsigned pk2(float lo, float hi) { f32x2 v = {lo, hi}; bf16x2_t b = __builtin_convertvector(v, bf16x2_t); return __builtin_bit_cast(unsigned, b); }
;     __device__ __forceinline__ void operator()(const AccT& acc, const Unit& u, int wr, int wc, int fr, int fq) const {
;     ...
; #pragma unroll
;         for (int ai = 0; ai < 2; ++ai)
; #pragma unroll
;             for (int m = 0; m < 4; ++m) {
;                 const int row = row0 + ai * HALF + m * 16;
;                 const float rs = rsv[ai * 4 + m];
;                 float v[8];
; #pragma unroll
;                 for (int n = 0; n < 2; ++n)
; #pragma unroll
;                     for (int j = 0; j < 4; ++j) {
;                         const float g = acc[ai][0][m][n][j] * rs, up = acc[ai][1][m][n][j] * rs;
;                         const float sg = __builtin_amdgcn_rcpf(1.0f + __builtin_amdgcn_exp2f(-g * LOG2E));
;                         v[4 * n + j] = g * sg * up;
;                     }
;                 u32x4 w; w.x = pk2(v[0], v[1]); w.y = pk2(v[2], v[3]); w.z = pk2(v[4], v[5]); w.w = pk2(v[6], v[7]);
;                 *(u32x4*)(mid + (size_t)row * FF + col0) = w;
;             }
	v_pk_mul_f32 v[82:83], v[88:89], v[150:151] op_sel_hi:[1,0]
	v_or_b32_e32 v94, 32, v153
	v_mul_f32_e32 v88, 0xbfb8aa3b, v82
	v_mul_f32_e32 v89, 0xbfb8aa3b, v83
	v_exp_f32_e32 v88, v88
	v_exp_f32_e32 v89, v89
	v_add_f32_e32 v88, 1.0, v88
	v_add_f32_e32 v89, 1.0, v89
	v_rcp_f32_e32 v88, v88
	v_rcp_f32_e32 v89, v89
	s_nop 0
	v_pk_mul_f32 v[82:83], v[82:83], v[88:89]
	s_nop 0
	v_pk_mul_f32 v[88:89], v[84:85], v[82:83]
	v_cvt_pk_bf16_f32 v84, v86, v87
	v_mad_i64_i32 v[86:87], s[46:47], v94, s39, v[118:119]
	v_cvt_pk_bf16_f32 v82, v90, v91
	v_cvt_pk_bf16_f32 v83, v92, v93
	v_cvt_pk_bf16_f32 v85, v88, v89
	v_lshl_add_u64 v[86:87], v[86:87], 0, v[120:121]
	global_store_dwordx4 v[86:87], v[82:85], off
	s_nop 1
	v_mul_f32_e32 v82, 0xbfb8aa3b, v78
	v_mul_f32_e32 v83, 0xbfb8aa3b, v79
	v_exp_f32_e32 v82, v82
	v_exp_f32_e32 v83, v83
	v_add_f32_e32 v82, 1.0, v82
	v_add_f32_e32 v83, 1.0, v83
	v_rcp_f32_e32 v82, v82
	v_rcp_f32_e32 v83, v83
	s_nop 0
	v_pk_mul_f32 v[78:79], v[78:79], v[82:83]
	s_nop 0
	v_pk_mul_f32 v[74:75], v[74:75], v[78:79]
	v_pk_mul_f32 v[78:79], v[80:81], v[148:149] op_sel_hi:[1,0]
	s_nop 0
	v_mul_f32_e32 v80, 0xbfb8aa3b, v78
	v_mul_f32_e32 v81, 0xbfb8aa3b, v79
	v_exp_f32_e32 v80, v80
	v_exp_f32_e32 v81, v81
	v_add_f32_e32 v80, 1.0, v80
	v_add_f32_e32 v81, 1.0, v81
	v_rcp_f32_e32 v80, v80
	v_rcp_f32_e32 v81, v81
	s_nop 0
	v_pk_mul_f32 v[78:79], v[78:79], v[80:81]
	s_nop 0
	v_pk_mul_f32 v[76:77], v[76:77], v[78:79]
	v_mul_f32_e32 v78, 0xbfb8aa3b, v70
	v_mul_f32_e32 v79, 0xbfb8aa3b, v71
	v_exp_f32_e32 v78, v78
	v_exp_f32_e32 v79, v79
	v_add_f32_e32 v78, 1.0, v78
	v_add_f32_e32 v79, 1.0, v79
	v_rcp_f32_e32 v78, v78
	v_rcp_f32_e32 v79, v79
	s_nop 0
	v_pk_mul_f32 v[70:71], v[70:71], v[78:79]
	s_nop 0
	v_pk_mul_f32 v[70:71], v[66:67], v[70:71]
	v_pk_mul_f32 v[66:67], v[72:73], v[148:149] op_sel_hi:[1,0]
	v_or_b32_e32 v78, 48, v153
	v_mul_f32_e32 v72, 0xbfb8aa3b, v66
	v_mul_f32_e32 v73, 0xbfb8aa3b, v67
	v_exp_f32_e32 v72, v72
	v_exp_f32_e32 v73, v73
	v_add_f32_e32 v72, 1.0, v72
	v_add_f32_e32 v73, 1.0, v73
	v_rcp_f32_e32 v72, v72
	v_rcp_f32_e32 v73, v73
	s_nop 0
	v_pk_mul_f32 v[66:67], v[66:67], v[72:73]
	s_nop 0
	v_pk_mul_f32 v[72:73], v[68:69], v[66:67]
	v_cvt_pk_bf16_f32 v68, v70, v71
	v_mad_i64_i32 v[70:71], s[46:47], v78, s39, v[118:119]
	v_cvt_pk_bf16_f32 v66, v74, v75
	v_cvt_pk_bf16_f32 v67, v76, v77
	v_cvt_pk_bf16_f32 v69, v72, v73
	v_lshl_add_u64 v[70:71], v[70:71], 0, v[120:121]
	global_store_dwordx4 v[70:71], v[66:69], off
	s_nop 1
	v_mul_f32_e32 v66, 0xbfb8aa3b, v62
	v_mul_f32_e32 v67, 0xbfb8aa3b, v63
	v_exp_f32_e32 v66, v66
	v_exp_f32_e32 v67, v67
	v_add_u32_e32 v68, 0x80, v153
	v_add_f32_e32 v66, 1.0, v66
	v_add_f32_e32 v67, 1.0, v67
	v_rcp_f32_e32 v66, v66
	v_rcp_f32_e32 v67, v67
	s_nop 0
	v_pk_mul_f32 v[62:63], v[62:63], v[66:67]
	s_nop 0
	v_pk_mul_f32 v[58:59], v[58:59], v[62:63]
	v_pk_mul_f32 v[62:63], v[64:65], v[146:147] op_sel_hi:[1,0]
	s_nop 0
	v_mul_f32_e32 v64, 0xbfb8aa3b, v62
	v_mul_f32_e32 v65, 0xbfb8aa3b, v63
	v_exp_f32_e32 v64, v64
	v_exp_f32_e32 v65, v65
	v_add_f32_e32 v64, 1.0, v64
	v_add_f32_e32 v65, 1.0, v65
	v_rcp_f32_e32 v64, v64
	v_rcp_f32_e32 v65, v65
	s_nop 0
	v_pk_mul_f32 v[62:63], v[62:63], v[64:65]
	s_nop 0
	v_pk_mul_f32 v[60:61], v[60:61], v[62:63]
	v_mul_f32_e32 v62, 0xbfb8aa3b, v54
	v_mul_f32_e32 v63, 0xbfb8aa3b, v55
	v_exp_f32_e32 v62, v62
	v_exp_f32_e32 v63, v63
	v_add_f32_e32 v62, 1.0, v62
	v_add_f32_e32 v63, 1.0, v63
	v_rcp_f32_e32 v62, v62
	v_rcp_f32_e32 v63, v63
	s_nop 0
	v_pk_mul_f32 v[54:55], v[54:55], v[62:63]
	s_nop 0
	v_pk_mul_f32 v[54:55], v[50:51], v[54:55]
	v_pk_mul_f32 v[50:51], v[56:57], v[146:147] op_sel_hi:[1,0]
	s_nop 0
	v_mul_f32_e32 v56, 0xbfb8aa3b, v50
	v_mul_f32_e32 v57, 0xbfb8aa3b, v51
	v_exp_f32_e32 v56, v56
	v_exp_f32_e32 v57, v57
	v_add_f32_e32 v56, 1.0, v56
	v_add_f32_e32 v57, 1.0, v57
	v_rcp_f32_e32 v56, v56
	v_rcp_f32_e32 v57, v57
	s_nop 0
	v_pk_mul_f32 v[50:51], v[50:51], v[56:57]
	s_nop 0
	v_pk_mul_f32 v[56:57], v[52:53], v[50:51]
	v_cvt_pk_bf16_f32 v52, v54, v55
	v_mad_i64_i32 v[54:55], s[46:47], v68, s39, v[118:119]
	v_cvt_pk_bf16_f32 v50, v58, v59
	v_cvt_pk_bf16_f32 v51, v60, v61
	v_cvt_pk_bf16_f32 v53, v56, v57
	v_lshl_add_u64 v[54:55], v[54:55], 0, v[120:121]
	global_store_dwordx4 v[54:55], v[50:53], off
	s_nop 1
	v_mul_f32_e32 v50, 0xbfb8aa3b, v46
	v_mul_f32_e32 v51, 0xbfb8aa3b, v47
	v_exp_f32_e32 v50, v50
	v_exp_f32_e32 v51, v51
	v_add_f32_e32 v50, 1.0, v50
	v_add_f32_e32 v51, 1.0, v51
	v_rcp_f32_e32 v50, v50
	v_rcp_f32_e32 v51, v51
	s_nop 0
	v_pk_mul_f32 v[46:47], v[46:47], v[50:51]
	s_nop 0
	v_pk_mul_f32 v[42:43], v[42:43], v[46:47]
	v_pk_mul_f32 v[46:47], v[48:49], v[144:145] op_sel_hi:[1,0]
	s_nop 0
	v_mul_f32_e32 v48, 0xbfb8aa3b, v46
	v_mul_f32_e32 v49, 0xbfb8aa3b, v47
	v_exp_f32_e32 v48, v48
	v_exp_f32_e32 v49, v49
	v_add_f32_e32 v48, 1.0, v48
; __device__ __forceinline__ unsigned pk2(float lo, float hi) { f32x2 v = {lo, hi}; bf16x2_t b = __builtin_convertvector(v, bf16x2_t); return __builtin_bit_cast(unsigned, b); }
; #define PG8_WAIT_V(n) asm volatile("s_waitcnt vmcnt(" #n ")" ::: "memory")
; #define PG8_BAR __builtin_amdgcn_s_barrier()
;     __device__ __forceinline__ void operator()(const AccT& acc, const Unit& u, int wr, int wc, int fr, int fq) const {
;     ...
; #pragma unroll
;         for (int ai = 0; ai < 2; ++ai)
; #pragma unroll
;             for (int m = 0; m < 4; ++m) {
;                 const int row = row0 + ai * HALF + m * 16;
;                 const float rs = rsv[ai * 4 + m];
;                 float v[8];
; #pragma unroll
;                 for (int n = 0; n < 2; ++n)
; #pragma unroll
;                     for (int j = 0; j < 4; ++j) {
;                         const float g = acc[ai][0][m][n][j] * rs, up = acc[ai][1][m][n][j] * rs;
;                         const float sg = __builtin_amdgcn_rcpf(1.0f + __builtin_amdgcn_exp2f(-g * LOG2E));
;                         v[4 * n + j] = g * sg * up;
;                     }
;                 u32x4 w; w.x = pk2(v[0], v[1]); w.y = pk2(v[2], v[3]); w.z = pk2(v[4], v[5]); w.w = pk2(v[6], v[7]);
;                 *(u32x4*)(mid + (size_t)row * FF + col0) = w;
;             }
; template <class Epi>
; __device__ __forceinline__ void gemm_phase(LAS unsigned char* lds, const Gemm g, const StaticOrder& S, const Epi& E) {
;     ...
;         E(acc, cur, wr, wc, fr, fq);
;         if (!has_next) break;
; #pragma unroll
;         for (int a = 0; a < 2; ++a)
; #pragma unroll
;             for (int b = 0; b < 2; ++b)
; #pragma unroll
;                 for (int m = 0; m < 4; ++m)
; #pragma unroll
;                     for (int n = 0; n < 2; ++n) acc[a][b][m][n] = (f32x4){0.f, 0.f, 0.f, 0.f};
;         cur = nxt; cA = nA; cB = nB; ++ui;
;     }
;     PG8_WAIT_V(0);
;     if (wr == 0) PG8_BAR;
;     PG8_BAR;
	v_add_f32_e32 v49, 1.0, v49
	v_rcp_f32_e32 v48, v48
	v_rcp_f32_e32 v49, v49
	s_nop 0
	v_pk_mul_f32 v[46:47], v[46:47], v[48:49]
	s_nop 0
	v_pk_mul_f32 v[44:45], v[44:45], v[46:47]
	v_mul_f32_e32 v46, 0xbfb8aa3b, v38
	v_mul_f32_e32 v47, 0xbfb8aa3b, v39
	v_exp_f32_e32 v46, v46
	v_exp_f32_e32 v47, v47
	v_add_f32_e32 v46, 1.0, v46
	v_add_f32_e32 v47, 1.0, v47
	v_rcp_f32_e32 v46, v46
	v_rcp_f32_e32 v47, v47
	s_nop 0
	v_pk_mul_f32 v[38:39], v[38:39], v[46:47]
	s_nop 0
	v_pk_mul_f32 v[38:39], v[34:35], v[38:39]
	v_pk_mul_f32 v[34:35], v[40:41], v[144:145] op_sel_hi:[1,0]
	v_add_u32_e32 v46, 0x90, v153
	v_mul_f32_e32 v40, 0xbfb8aa3b, v34
	v_mul_f32_e32 v41, 0xbfb8aa3b, v35
	v_exp_f32_e32 v40, v40
	v_exp_f32_e32 v41, v41
	v_add_f32_e32 v40, 1.0, v40
	v_add_f32_e32 v41, 1.0, v41
	v_rcp_f32_e32 v40, v40
	v_rcp_f32_e32 v41, v41
	s_nop 0
	v_pk_mul_f32 v[34:35], v[34:35], v[40:41]
	s_nop 0
	v_pk_mul_f32 v[40:41], v[36:37], v[34:35]
	v_cvt_pk_bf16_f32 v36, v38, v39
	v_mad_i64_i32 v[38:39], s[46:47], v46, s39, v[118:119]
	v_cvt_pk_bf16_f32 v34, v42, v43
	v_cvt_pk_bf16_f32 v35, v44, v45
	v_cvt_pk_bf16_f32 v37, v40, v41
	v_lshl_add_u64 v[38:39], v[38:39], 0, v[120:121]
	global_store_dwordx4 v[38:39], v[34:37], off
	s_nop 1
	v_mul_f32_e32 v34, 0xbfb8aa3b, v30
	v_mul_f32_e32 v35, 0xbfb8aa3b, v31
	v_exp_f32_e32 v34, v34
	v_exp_f32_e32 v35, v35
	v_add_f32_e32 v34, 1.0, v34
	v_add_f32_e32 v35, 1.0, v35
	v_rcp_f32_e32 v34, v34
	v_rcp_f32_e32 v35, v35
	s_nop 0
	v_pk_mul_f32 v[30:31], v[30:31], v[34:35]
	s_nop 0
	v_pk_mul_f32 v[26:27], v[26:27], v[30:31]
	v_pk_mul_f32 v[30:31], v[32:33], v[142:143] op_sel_hi:[1,0]
	s_nop 0
	v_mul_f32_e32 v32, 0xbfb8aa3b, v30
	v_mul_f32_e32 v33, 0xbfb8aa3b, v31
	v_exp_f32_e32 v32, v32
	v_exp_f32_e32 v33, v33
	v_add_f32_e32 v32, 1.0, v32
	v_add_f32_e32 v33, 1.0, v33
	v_rcp_f32_e32 v32, v32
	v_rcp_f32_e32 v33, v33
	s_nop 0
	v_pk_mul_f32 v[30:31], v[30:31], v[32:33]
	s_nop 0
	v_pk_mul_f32 v[28:29], v[28:29], v[30:31]
	v_mul_f32_e32 v30, 0xbfb8aa3b, v22
	v_mul_f32_e32 v31, 0xbfb8aa3b, v23
	v_exp_f32_e32 v30, v30
	v_exp_f32_e32 v31, v31
	v_add_f32_e32 v30, 1.0, v30
	v_add_f32_e32 v31, 1.0, v31
	v_rcp_f32_e32 v30, v30
	v_rcp_f32_e32 v31, v31
	s_nop 0
	v_pk_mul_f32 v[22:23], v[22:23], v[30:31]
	s_nop 0
	v_pk_mul_f32 v[22:23], v[18:19], v[22:23]
	v_pk_mul_f32 v[18:19], v[24:25], v[142:143] op_sel_hi:[1,0]
	v_add_u32_e32 v30, 0xa0, v153
	v_mul_f32_e32 v24, 0xbfb8aa3b, v18
	v_mul_f32_e32 v25, 0xbfb8aa3b, v19
	v_exp_f32_e32 v24, v24
	v_exp_f32_e32 v25, v25
	v_add_f32_e32 v24, 1.0, v24
	v_add_f32_e32 v25, 1.0, v25
	v_rcp_f32_e32 v24, v24
	v_rcp_f32_e32 v25, v25
	s_nop 0
	v_pk_mul_f32 v[18:19], v[18:19], v[24:25]
	s_nop 0
	v_pk_mul_f32 v[24:25], v[20:21], v[18:19]
	v_cvt_pk_bf16_f32 v20, v22, v23
	v_mad_i64_i32 v[22:23], s[46:47], v30, s39, v[118:119]
	v_cvt_pk_bf16_f32 v18, v26, v27
	v_cvt_pk_bf16_f32 v19, v28, v29
	v_cvt_pk_bf16_f32 v21, v24, v25
	v_lshl_add_u64 v[22:23], v[22:23], 0, v[120:121]
	global_store_dwordx4 v[22:23], v[18:21], off
	s_nop 1
	v_mul_f32_e32 v18, 0xbfb8aa3b, v14
	v_mul_f32_e32 v19, 0xbfb8aa3b, v15
	v_exp_f32_e32 v18, v18
	v_exp_f32_e32 v19, v19
	v_add_f32_e32 v18, 1.0, v18
	v_add_f32_e32 v19, 1.0, v19
	v_rcp_f32_e32 v18, v18
	v_rcp_f32_e32 v19, v19
	s_nop 0
	v_pk_mul_f32 v[14:15], v[14:15], v[18:19]
	s_nop 0
	v_pk_mul_f32 v[10:11], v[10:11], v[14:15]
	v_pk_mul_f32 v[14:15], v[16:17], v[140:141] op_sel_hi:[1,0]
	s_nop 0
	v_mul_f32_e32 v16, 0xbfb8aa3b, v14
	v_mul_f32_e32 v17, 0xbfb8aa3b, v15
	v_exp_f32_e32 v16, v16
	v_exp_f32_e32 v17, v17
	v_add_f32_e32 v16, 1.0, v16
	v_add_f32_e32 v17, 1.0, v17
	v_rcp_f32_e32 v16, v16
	v_rcp_f32_e32 v17, v17
	s_nop 0
	v_pk_mul_f32 v[14:15], v[14:15], v[16:17]
	s_nop 0
	v_pk_mul_f32 v[12:13], v[12:13], v[14:15]
	v_mul_f32_e32 v14, 0xbfb8aa3b, v6
	v_mul_f32_e32 v15, 0xbfb8aa3b, v7
	v_exp_f32_e32 v14, v14
	v_exp_f32_e32 v15, v15
	v_add_f32_e32 v14, 1.0, v14
	v_add_f32_e32 v15, 1.0, v15
	v_rcp_f32_e32 v14, v14
	v_rcp_f32_e32 v15, v15
	s_nop 0
	v_pk_mul_f32 v[6:7], v[6:7], v[14:15]
	s_nop 0
	v_pk_mul_f32 v[6:7], v[2:3], v[6:7]
	v_pk_mul_f32 v[2:3], v[8:9], v[140:141] op_sel_hi:[1,0]
	v_add_u32_e32 v14, 0xb0, v153
	v_mul_f32_e32 v8, 0xbfb8aa3b, v2
	v_mul_f32_e32 v9, 0xbfb8aa3b, v3
	v_exp_f32_e32 v8, v8
	v_exp_f32_e32 v9, v9
	v_add_f32_e32 v8, 1.0, v8
	v_add_f32_e32 v9, 1.0, v9
	v_rcp_f32_e32 v8, v8
	v_rcp_f32_e32 v9, v9
	s_nop 0
	v_pk_mul_f32 v[2:3], v[2:3], v[8:9]
	s_nop 0
	v_pk_mul_f32 v[8:9], v[4:5], v[2:3]
	v_cvt_pk_bf16_f32 v4, v6, v7
	v_mad_i64_i32 v[6:7], s[46:47], v14, s39, v[118:119]
	v_cvt_pk_bf16_f32 v2, v10, v11
	v_cvt_pk_bf16_f32 v3, v12, v13
	v_cvt_pk_bf16_f32 v5, v8, v9
	v_lshl_add_u64 v[6:7], v[6:7], 0, v[120:121]
	s_mov_b64 s[46:47], s[42:43]
	global_store_dwordx4 v[6:7], v[2:5], off
	s_cbranch_vccz .LBB0_87
	s_waitcnt vmcnt(0)
	s_cmpk_gt_u32 s52, 0xff
	s_cbranch_scc1 .LBB0_94
	s_barrier

; #define PG8_STAGE(bufoff, gbase, voff) do { _Pragma("unroll") for (int _i = 0; _i < 2; ++_i) \
;         __builtin_amdgcn_global_load_lds((const unsigned*)((const char*)(gbase) + (voff)[_i]), (LAS unsigned*)(lds + (bufoff) + ldsw + _i * 8192), 16, 0, 0); } while (0)
; #define PG8_LDA(dst, b, h) do { _Pragma("unroll") for (int m = 0; m < 4; ++m) _Pragma("unroll") for (int k = 0; k < 2; ++k) dst[m][k] = *(const LAS bf16x8*)(lds + PG8_SA(b, h) + aoff + m * 2048 + k * 1024); } while (0)
; #define PG8_LDB(dst, b, h) do { _Pragma("unroll") for (int n = 0; n < 2; ++n) _Pragma("unroll") for (int k = 0; k < 2; ++k) dst[n][k] = *(const LAS bf16x8*)(lds + PG8_SB(b, h) + boff + n * 2048 + k * 1024); } while (0)
; #define PG8_MMA(ai, bj, At, Bt) do { __builtin_amdgcn_s_setprio(1); _Pragma("unroll") for (int m = 0; m < 4; ++m) _Pragma("unroll") for (int n = 0; n < 2; ++n) _Pragma("unroll") for (int k = 0; k < 2; ++k) \
;         acc[ai][bj][m][n] = __builtin_amdgcn_mfma_f32_16x16x32_bf16(Bt[n][k], At[m][k], acc[ai][bj][m][n], 0, 0, 0); __builtin_amdgcn_s_setprio(0); } while (0)
; #define PG8_WAIT_V(n) asm volatile("s_waitcnt vmcnt(" #n ")" ::: "memory")
; template <class Epi>
; __device__ __forceinline__ void gemm_phase(LAS unsigned char* lds, const Gemm g, const StaticOrder& S, const Epi& E) {
;     ...
;         for (int t = 0; t < nt; t += 2) {
;             const bool last = (t == nt - 2);
;             const char* a1 = cA + (size_t)(t + 1) * kstep;
;             const char* a2 = last ? nA : cA + (size_t)(t + 2) * kstep; const char* b2 = last ? nB : cB + (size_t)(t + 2) * kstep;
;             const char* a3 = a2 + kstep; const char* b3 = b2 + kstep;
;             PG8_LDB(B0, 0, 0); PG8_SCHED; PG8_LDA(At, 0, 0); PG8_STAGE(PG8_SA(1, 1), a1 + hstep, voffA);
;             PG8_WAIT_L(8); PG8_BAR; PG8_WAIT_L(0); PG8_MMA(0, 0, At, B0); PG8_BAR; PG8_SCHED;
;             PG8_LDB(B1, 0, 1); PG8_STAGE(PG8_SB(0, 0), b2, voffB);
;             PG8_BAR; PG8_WAIT_L(0); PG8_MMA(0, 1, At, B1); PG8_BAR;
;             PG8_LDA(At, 0, 1); PG8_STAGE(PG8_SA(0, 0), a2, voffA);
;             PG8_BAR; PG8_WAIT_L(0); PG8_MMA(1, 0, At, B0); PG8_BAR; PG8_SCHED;
;             PG8_STAGE(PG8_SB(0, 1), b2 + hstep, voffB);
;             PG8_WAIT_V(6); PG8_BAR; PG8_MMA(1, 1, At, B1); PG8_BAR;
;             PG8_LDB(B0, 1, 0); PG8_SCHED; PG8_LDA(At, 1, 0); PG8_STAGE(PG8_SA(0, 1), a2 + hstep, voffA);
.LBB0_654:
	s_add_i32 s84, s62, 2
	s_add_u32 s64, s60, 0x80
	s_addc_u32 s63, s61, 0
	s_add_i32 s85, 0, 0x10000
	s_cmp_eq_u32 s77, s62
	s_cselect_b32 s62, s2, s64
	s_cselect_b32 s63, s3, s63
	s_cselect_b32 s65, s41, s83
	s_cselect_b32 s64, s40, s82
	s_add_i32 m0, s70, 0xc000
	ds_read_b128 v[146:149], v243
	ds_read_b128 v[150:153], v243 offset:1024
	ds_read_b128 v[154:157], v243 offset:2048
	ds_read_b128 v[158:161], v243 offset:3072
	ds_read_b128 v[162:165], v243 offset:4096
	ds_read_b128 v[166:169], v243 offset:5120
	ds_read_b128 v[170:173], v243 offset:6144
	ds_read_b128 v[174:177], v243 offset:7168
	global_load_lds_dwordx4 v214, s[60:61]
	s_add_i32 m0, s70, 0xe000
	s_waitcnt lgkmcnt(8)
	global_load_lds_dwordx4 v216, s[60:61]
	s_barrier
	s_waitcnt lgkmcnt(0)
	v_mfma_f32_16x16x32_bf16 v[142:145], v[58:61], v[146:149], v[142:145]
	v_mfma_f32_16x16x32_bf16 v[138:141], v[66:69], v[146:149], v[138:141]
	v_mfma_f32_16x16x32_bf16 v[126:129], v[58:61], v[154:157], v[126:129]
	v_mfma_f32_16x16x32_bf16 v[122:125], v[66:69], v[154:157], v[122:125]
	v_mfma_f32_16x16x32_bf16 v[110:113], v[58:61], v[162:165], v[110:113]
	v_mfma_f32_16x16x32_bf16 v[106:109], v[66:69], v[162:165], v[106:109]
	v_mfma_f32_16x16x32_bf16 v[94:97], v[58:61], v[170:173], v[94:97]
	v_mfma_f32_16x16x32_bf16 v[90:93], v[66:69], v[170:173], v[90:93]
	v_mfma_f32_16x16x32_bf16 v[142:145], v[62:65], v[150:153], v[142:145]
	v_mfma_f32_16x16x32_bf16 v[138:141], v[70:73], v[150:153], v[138:141]
	v_mfma_f32_16x16x32_bf16 v[126:129], v[62:65], v[158:161], v[126:129]
	v_mfma_f32_16x16x32_bf16 v[122:125], v[70:73], v[158:161], v[122:125]
	v_mfma_f32_16x16x32_bf16 v[110:113], v[62:65], v[166:169], v[110:113]
	v_mfma_f32_16x16x32_bf16 v[106:109], v[70:73], v[166:169], v[106:109]
	v_mfma_f32_16x16x32_bf16 v[94:97], v[62:65], v[174:177], v[94:97]
	v_mfma_f32_16x16x32_bf16 v[90:93], v[70:73], v[174:177], v[90:93]
	s_barrier
	s_add_i32 s85, s85, s69
	s_add_u32 s98, s64, s22
	s_addc_u32 s99, s65, s23
	s_mov_b32 m0, s85
	ds_read_b128 v[178:181], v194 offset:16384
	ds_read_b128 v[182:185], v194 offset:17408
	ds_read_b128 v[186:189], v194 offset:18432
	ds_read_b128 v[190:193], v194 offset:19456
	global_load_lds_dwordx4 v0, s[64:65]
	s_add_i32 m0, s85, 0x2000
	s_add_i32 s86, 0, 0x14000
	global_load_lds_dwordx4 v208, s[64:65]
	s_barrier
	s_waitcnt lgkmcnt(0)
	v_mfma_f32_16x16x32_bf16 v[134:137], v[178:181], v[146:149], v[134:137]
	v_mfma_f32_16x16x32_bf16 v[130:133], v[186:189], v[146:149], v[130:133]
	v_mfma_f32_16x16x32_bf16 v[118:121], v[178:181], v[154:157], v[118:121]
	v_mfma_f32_16x16x32_bf16 v[114:117], v[186:189], v[154:157], v[114:117]
	v_mfma_f32_16x16x32_bf16 v[102:105], v[178:181], v[162:165], v[102:105]
	v_mfma_f32_16x16x32_bf16 v[98:101], v[186:189], v[162:165], v[98:101]
	v_mfma_f32_16x16x32_bf16 v[86:89], v[178:181], v[170:173], v[86:89]
	v_mfma_f32_16x16x32_bf16 v[82:85], v[186:189], v[170:173], v[82:85]
	v_mfma_f32_16x16x32_bf16 v[134:137], v[182:185], v[150:153], v[134:137]
	v_mfma_f32_16x16x32_bf16 v[130:133], v[190:193], v[150:153], v[130:133]
	v_mfma_f32_16x16x32_bf16 v[118:121], v[182:185], v[158:161], v[118:121]
	v_mfma_f32_16x16x32_bf16 v[114:117], v[190:193], v[158:161], v[114:117]
	v_mfma_f32_16x16x32_bf16 v[102:105], v[182:185], v[166:169], v[102:105]
	v_mfma_f32_16x16x32_bf16 v[98:101], v[190:193], v[166:169], v[98:101]
	v_mfma_f32_16x16x32_bf16 v[86:89], v[182:185], v[174:177], v[86:89]
	v_mfma_f32_16x16x32_bf16 v[82:85], v[190:193], v[174:177], v[82:85]
	s_barrier
	ds_read_b128 v[146:149], v243 offset:16384
	ds_read_b128 v[150:153], v243 offset:17408
	ds_read_b128 v[154:157], v243 offset:18432
	ds_read_b128 v[158:161], v243 offset:19456
	ds_read_b128 v[162:165], v243 offset:20480
	ds_read_b128 v[166:169], v243 offset:21504
	ds_read_b128 v[170:173], v243 offset:22528
	s_mov_b32 m0, s70
	s_add_u32 s100, s62, s22
	s_addc_u32 s101, s63, s23
	ds_read_b128 v[174:177], v243 offset:23552
	global_load_lds_dwordx4 v212, s[62:63]
	s_mov_b32 m0, s71
	s_waitcnt vmcnt(9)
	global_load_lds_dwordx4 v210, s[62:63]
	s_barrier
	s_waitcnt lgkmcnt(0)
	v_mfma_f32_16x16x32_bf16 v[78:81], v[58:61], v[146:149], v[78:81]
	v_mfma_f32_16x16x32_bf16 v[74:77], v[66:69], v[146:149], v[74:77]
	v_mfma_f32_16x16x32_bf16 v[46:49], v[58:61], v[154:157], v[46:49]
	v_mfma_f32_16x16x32_bf16 v[42:45], v[66:69], v[154:157], v[42:45]
	v_mfma_f32_16x16x32_bf16 v[30:33], v[58:61], v[162:165], v[30:33]
	v_mfma_f32_16x16x32_bf16 v[26:29], v[66:69], v[162:165], v[26:29]
	v_mfma_f32_16x16x32_bf16 v[14:17], v[58:61], v[170:173], v[14:17]
	v_mfma_f32_16x16x32_bf16 v[10:13], v[66:69], v[170:173], v[10:13]
	v_mfma_f32_16x16x32_bf16 v[78:81], v[62:65], v[150:153], v[78:81]
	v_mfma_f32_16x16x32_bf16 v[74:77], v[70:73], v[150:153], v[74:77]
	v_mfma_f32_16x16x32_bf16 v[46:49], v[62:65], v[158:161], v[46:49]
	v_mfma_f32_16x16x32_bf16 v[42:45], v[70:73], v[158:161], v[42:45]
	v_mfma_f32_16x16x32_bf16 v[30:33], v[62:65], v[166:169], v[30:33]
	v_mfma_f32_16x16x32_bf16 v[26:29], v[70:73], v[166:169], v[26:29]
	v_mfma_f32_16x16x32_bf16 v[14:17], v[62:65], v[174:177], v[14:17]
	v_mfma_f32_16x16x32_bf16 v[10:13], v[70:73], v[174:177], v[10:13]
	s_barrier
	ds_read_b128 v[58:61], v194 offset:32768
	ds_read_b128 v[62:65], v194 offset:33792
	ds_read_b128 v[66:69], v194 offset:34816
	ds_read_b128 v[70:73], v194 offset:35840
	s_add_u32 s64, s64, s50
	s_addc_u32 s65, s65, 0
	s_add_i32 s85, s86, s69
	s_mov_b32 m0, s85
	s_add_u32 vcc_lo, s64, s22
	s_addc_u32 vcc_hi, s65, s23
	global_load_lds_dwordx4 v0, s[64:65]
	s_add_i32 m0, s85, 0x2000
	s_waitcnt vmcnt(5)
	global_load_lds_dwordx4 v208, s[64:65]
	s_barrier
; #define PG8_STAGE(bufoff, gbase, voff) do { _Pragma("unroll") for (int _i = 0; _i < 2; ++_i) \
;         __builtin_amdgcn_global_load_lds((const unsigned*)((const char*)(gbase) + (voff)[_i]), (LAS unsigned*)(lds + (bufoff) + ldsw + _i * 8192), 16, 0, 0); } while (0)
; #define PG8_LDA(dst, b, h) do { _Pragma("unroll") for (int m = 0; m < 4; ++m) _Pragma("unroll") for (int k = 0; k < 2; ++k) dst[m][k] = *(const LAS bf16x8*)(lds + PG8_SA(b, h) + aoff + m * 2048 + k * 1024); } while (0)
; #define PG8_LDB(dst, b, h) do { _Pragma("unroll") for (int n = 0; n < 2; ++n) _Pragma("unroll") for (int k = 0; k < 2; ++k) dst[n][k] = *(const LAS bf16x8*)(lds + PG8_SB(b, h) + boff + n * 2048 + k * 1024); } while (0)
; #define PG8_MMA(ai, bj, At, Bt) do { __builtin_amdgcn_s_setprio(1); _Pragma("unroll") for (int m = 0; m < 4; ++m) _Pragma("unroll") for (int n = 0; n < 2; ++n) _Pragma("unroll") for (int k = 0; k < 2; ++k) \
;         acc[ai][bj][m][n] = __builtin_amdgcn_mfma_f32_16x16x32_bf16(Bt[n][k], At[m][k], acc[ai][bj][m][n], 0, 0, 0); __builtin_amdgcn_s_setprio(0); } while (0)
; #define PG8_WAIT_V(n) asm volatile("s_waitcnt vmcnt(" #n ")" ::: "memory")
; #define PG8_WAIT_L(n) asm volatile("s_waitcnt lgkmcnt(" #n ")" ::: "memory")
; #define PG8_BAR __builtin_amdgcn_s_barrier()
; #define PG8_SCHED __builtin_amdgcn_sched_barrier(0)
; template <class Epi>
; __device__ __forceinline__ void gemm_phase(LAS unsigned char* lds, const Gemm g, const StaticOrder& S, const Epi& E) {
;     ...
;             PG8_LDB(B0, 1, 0); PG8_SCHED; PG8_LDA(At, 1, 0); PG8_STAGE(PG8_SA(0, 1), a2 + hstep, voffA);
;             PG8_WAIT_L(8); PG8_BAR; PG8_WAIT_L(0); PG8_MMA(0, 0, At, B0); PG8_BAR; PG8_SCHED;
;             PG8_LDB(B1, 1, 1); PG8_STAGE(PG8_SB(1, 0), b3, voffB);
;             PG8_BAR; PG8_WAIT_L(0); PG8_MMA(0, 1, At, B1); PG8_BAR;
;             PG8_LDA(At, 1, 1); PG8_STAGE(PG8_SA(1, 0), a3, voffA);
;             PG8_BAR; PG8_WAIT_L(0); PG8_MMA(1, 0, At, B0); PG8_BAR; PG8_SCHED;
;             PG8_STAGE(PG8_SB(1, 1), b3 + hstep, voffB);
;             PG8_WAIT_V(6); PG8_BAR; PG8_MMA(1, 1, At, B1); PG8_BAR;
	v_mfma_f32_16x16x32_bf16 v[54:57], v[178:181], v[146:149], v[54:57]
	v_mfma_f32_16x16x32_bf16 v[50:53], v[186:189], v[146:149], v[50:53]
	v_mfma_f32_16x16x32_bf16 v[38:41], v[178:181], v[154:157], v[38:41]
	v_mfma_f32_16x16x32_bf16 v[34:37], v[186:189], v[154:157], v[34:37]
	v_mfma_f32_16x16x32_bf16 v[22:25], v[178:181], v[162:165], v[22:25]
	v_mfma_f32_16x16x32_bf16 v[18:21], v[186:189], v[162:165], v[18:21]
	v_mfma_f32_16x16x32_bf16 v[6:9], v[178:181], v[170:173], v[6:9]
	v_mfma_f32_16x16x32_bf16 v[2:5], v[186:189], v[170:173], v[2:5]
	v_mfma_f32_16x16x32_bf16 v[54:57], v[182:185], v[150:153], v[54:57]
	v_mfma_f32_16x16x32_bf16 v[50:53], v[190:193], v[150:153], v[50:53]
	v_mfma_f32_16x16x32_bf16 v[38:41], v[182:185], v[158:161], v[38:41]
	v_mfma_f32_16x16x32_bf16 v[34:37], v[190:193], v[158:161], v[34:37]
	v_mfma_f32_16x16x32_bf16 v[22:25], v[182:185], v[166:169], v[22:25]
	v_mfma_f32_16x16x32_bf16 v[18:21], v[190:193], v[166:169], v[18:21]
	v_mfma_f32_16x16x32_bf16 v[6:9], v[182:185], v[174:177], v[6:9]
	v_mfma_f32_16x16x32_bf16 v[2:5], v[190:193], v[174:177], v[2:5]
	s_barrier
	s_add_u32 s62, s62, s50
	s_addc_u32 s63, s63, 0
	s_mov_b32 m0, s72
	ds_read_b128 v[146:149], v243 offset:32768
	ds_read_b128 v[150:153], v243 offset:33792
	ds_read_b128 v[154:157], v243 offset:34816
	ds_read_b128 v[158:161], v243 offset:35840
	ds_read_b128 v[162:165], v243 offset:36864
	ds_read_b128 v[166:169], v243 offset:37888
	ds_read_b128 v[170:173], v243 offset:38912
	s_add_i32 s64, 0, 0x18000
	ds_read_b128 v[174:177], v243 offset:39936
	global_load_lds_dwordx4 v212, s[62:63]
	s_mov_b32 m0, s73
	s_waitcnt lgkmcnt(8)
	global_load_lds_dwordx4 v210, s[62:63]
	s_barrier
	s_waitcnt lgkmcnt(0)
	v_mfma_f32_16x16x32_bf16 v[142:145], v[58:61], v[146:149], v[142:145]
	v_mfma_f32_16x16x32_bf16 v[138:141], v[66:69], v[146:149], v[138:141]
	v_mfma_f32_16x16x32_bf16 v[126:129], v[58:61], v[154:157], v[126:129]
	v_mfma_f32_16x16x32_bf16 v[122:125], v[66:69], v[154:157], v[122:125]
	v_mfma_f32_16x16x32_bf16 v[110:113], v[58:61], v[162:165], v[110:113]
	v_mfma_f32_16x16x32_bf16 v[106:109], v[66:69], v[162:165], v[106:109]
	v_mfma_f32_16x16x32_bf16 v[94:97], v[58:61], v[170:173], v[94:97]
	v_mfma_f32_16x16x32_bf16 v[90:93], v[66:69], v[170:173], v[90:93]
	v_mfma_f32_16x16x32_bf16 v[142:145], v[62:65], v[150:153], v[142:145]
	v_mfma_f32_16x16x32_bf16 v[138:141], v[70:73], v[150:153], v[138:141]
	v_mfma_f32_16x16x32_bf16 v[126:129], v[62:65], v[158:161], v[126:129]
	v_mfma_f32_16x16x32_bf16 v[122:125], v[70:73], v[158:161], v[122:125]
	v_mfma_f32_16x16x32_bf16 v[110:113], v[62:65], v[166:169], v[110:113]
	v_mfma_f32_16x16x32_bf16 v[106:109], v[70:73], v[166:169], v[106:109]
	v_mfma_f32_16x16x32_bf16 v[94:97], v[62:65], v[174:177], v[94:97]
	v_mfma_f32_16x16x32_bf16 v[90:93], v[70:73], v[174:177], v[90:93]
	s_barrier
	s_add_i32 s63, s64, s69
	s_mov_b32 m0, s63
	ds_read_b128 v[178:181], v194 offset:49152
	ds_read_b128 v[182:185], v194 offset:50176
	ds_read_b128 v[186:189], v194 offset:51200
	ds_read_b128 v[190:193], v194 offset:52224
	global_load_lds_dwordx4 v0, s[98:99]
	s_add_i32 m0, s63, 0x2000
	s_add_i32 s62, 0, 0x1c000
	global_load_lds_dwordx4 v208, s[98:99]
	s_barrier
	s_waitcnt lgkmcnt(0)
	v_mfma_f32_16x16x32_bf16 v[134:137], v[178:181], v[146:149], v[134:137]
	v_mfma_f32_16x16x32_bf16 v[130:133], v[186:189], v[146:149], v[130:133]
	v_mfma_f32_16x16x32_bf16 v[118:121], v[178:181], v[154:157], v[118:121]
	v_mfma_f32_16x16x32_bf16 v[114:117], v[186:189], v[154:157], v[114:117]
	v_mfma_f32_16x16x32_bf16 v[102:105], v[178:181], v[162:165], v[102:105]
	v_mfma_f32_16x16x32_bf16 v[98:101], v[186:189], v[162:165], v[98:101]
	v_mfma_f32_16x16x32_bf16 v[86:89], v[178:181], v[170:173], v[86:89]
	v_mfma_f32_16x16x32_bf16 v[82:85], v[186:189], v[170:173], v[82:85]
	v_mfma_f32_16x16x32_bf16 v[134:137], v[182:185], v[150:153], v[134:137]
	v_mfma_f32_16x16x32_bf16 v[130:133], v[190:193], v[150:153], v[130:133]
	v_mfma_f32_16x16x32_bf16 v[118:121], v[182:185], v[158:161], v[118:121]
	v_mfma_f32_16x16x32_bf16 v[114:117], v[190:193], v[158:161], v[114:117]
	v_mfma_f32_16x16x32_bf16 v[102:105], v[182:185], v[166:169], v[102:105]
	v_mfma_f32_16x16x32_bf16 v[98:101], v[190:193], v[166:169], v[98:101]
	v_mfma_f32_16x16x32_bf16 v[86:89], v[182:185], v[174:177], v[86:89]
	v_mfma_f32_16x16x32_bf16 v[82:85], v[190:193], v[174:177], v[82:85]
	s_barrier
	ds_read_b128 v[146:149], v243 offset:49152
	ds_read_b128 v[150:153], v243 offset:50176
	ds_read_b128 v[154:157], v243 offset:51200
	ds_read_b128 v[158:161], v243 offset:52224
	ds_read_b128 v[162:165], v243 offset:53248
	ds_read_b128 v[166:169], v243 offset:54272
	ds_read_b128 v[170:173], v243 offset:55296
	s_mov_b32 m0, s75
	ds_read_b128 v[174:177], v243 offset:56320
	global_load_lds_dwordx4 v212, s[100:101]
	s_mov_b32 m0, s76
	s_waitcnt vmcnt(9)
	global_load_lds_dwordx4 v210, s[100:101]
	s_barrier
	s_waitcnt lgkmcnt(0)
	v_mfma_f32_16x16x32_bf16 v[78:81], v[58:61], v[146:149], v[78:81]
	v_mfma_f32_16x16x32_bf16 v[74:77], v[66:69], v[146:149], v[74:77]
	v_mfma_f32_16x16x32_bf16 v[46:49], v[58:61], v[154:157], v[46:49]
	v_mfma_f32_16x16x32_bf16 v[42:45], v[66:69], v[154:157], v[42:45]
	v_mfma_f32_16x16x32_bf16 v[30:33], v[58:61], v[162:165], v[30:33]
	v_mfma_f32_16x16x32_bf16 v[26:29], v[66:69], v[162:165], v[26:29]
	v_mfma_f32_16x16x32_bf16 v[14:17], v[58:61], v[170:173], v[14:17]
	v_mfma_f32_16x16x32_bf16 v[10:13], v[66:69], v[170:173], v[10:13]
	v_mfma_f32_16x16x32_bf16 v[78:81], v[62:65], v[150:153], v[78:81]
	v_mfma_f32_16x16x32_bf16 v[74:77], v[70:73], v[150:153], v[74:77]
	v_mfma_f32_16x16x32_bf16 v[46:49], v[62:65], v[158:161], v[46:49]
	v_mfma_f32_16x16x32_bf16 v[42:45], v[70:73], v[158:161], v[42:45]
	v_mfma_f32_16x16x32_bf16 v[30:33], v[62:65], v[166:169], v[30:33]
	v_mfma_f32_16x16x32_bf16 v[26:29], v[70:73], v[166:169], v[26:29]
	v_mfma_f32_16x16x32_bf16 v[14:17], v[62:65], v[174:177], v[14:17]
	v_mfma_f32_16x16x32_bf16 v[10:13], v[70:73], v[174:177], v[10:13]
	s_barrier
; #define PG8_WAIT_V(n) asm volatile("s_waitcnt vmcnt(" #n ")" ::: "memory")
;     __device__ __forceinline__ void operator()(const AccT& acc, const Unit& u, int wr, int wc, int fr, int fq) const {
;         const int row0 = u.pm * BM + wr * 64 + fr, col0 = u.pn * BM + wc * 32 + 8 * fq;
;         f32x4 gv[2][2];
; #pragma unroll
;         for (int bj = 0; bj < 2; ++bj)
; #pragma unroll
;             for (int n = 0; n < 2; ++n) gv[bj][n] = *(const f32x4*)(g + col0 + bj * HALF + 4 * n);
; #pragma unroll
;         for (int ai = 0; ai < 2; ++ai) {
;             f32x4 xv[4][2][2];
; #pragma unroll
;             for (int m = 0; m < 4; ++m)
; #pragma unroll
;                 for (int bj = 0; bj < 2; ++bj) {
;                     const size_t p = (size_t)(row0 + ai * HALF + m * 16) * DM + col0 + bj * HALF;
;                     xv[m][bj][0] = __builtin_nontemporal_load((const f32x4*)(xin + p)); xv[m][bj][1] = __builtin_nontemporal_load((const f32x4*)(xin + p + 4));
;                 }
; #pragma unroll
;             for (int m = 0; m < 4; ++m) {
;                 const int row = row0 + ai * HALF + m * 16;
;                 float ssa = 0.f;
; #pragma unroll
;                 for (int bj = 0; bj < 2; ++bj) {
;                     const size_t p = (size_t)row * DM + col0 + bj * HALF;
;                     const f32x4 x0 = xv[m][bj][0] + acc[ai][bj][m][0] * alpha, x1 = xv[m][bj][1] + acc[ai][bj][m][1] * alpha;
;                     __builtin_nontemporal_store(x0, (f32x4*)(xout + p)); __builtin_nontemporal_store(x1, (f32x4*)(xout + p + 4));
;                     ssa += (x0[0] * x0[0] + x0[1] * x0[1]) + (x0[2] * x0[2] + x0[3] * x0[3]) + (x1[0] * x1[0] + x1[1] * x1[1]) + (x1[2] * x1[2] + x1[3] * x1[3]);
;                     const f32x4 h0 = x0 * gv[bj][0], h1 = x1 * gv[bj][1];
;                     u32x4 w; w.x = pk2(h0[0], h0[1]); w.y = pk2(h0[2], h0[3]); w.z = pk2(h1[0], h1[1]); w.w = pk2(h1[2], h1[3]);
;                     *(u32x4*)(h + p) = w;
;                 }
;                 ssa += __shfl_xor(ssa, 16); ssa += __shfl_xor(ssa, 32);
;                 if (fq == 0) unsafeAtomicAdd(ssout + row, ssa);
; template <class Epi>
; __device__ __forceinline__ void gemm_phase(LAS unsigned char* lds, const Gemm g, const StaticOrder& S, const Epi& E) {
;     ...
;             PG8_WAIT_V(6); PG8_BAR; PG8_MMA(1, 1, At, B1); PG8_BAR;
;         }
;         E(acc, cur, wr, wc, fr, fq);
	ds_read_b128 v[58:61], v194
	ds_read_b128 v[62:65], v194 offset:1024
	ds_read_b128 v[66:69], v194 offset:2048
	s_add_u32 s60, s60, 0x100
	s_addc_u32 s61, s61, 0
	s_add_u32 s82, s82, 0x100
	s_addc_u32 s83, s83, 0
	ds_read_b128 v[70:73], v194 offset:3072
	s_add_i32 s62, s62, s69
	s_mov_b32 m0, s62
	s_nop 0
	global_load_lds_dwordx4 v0, vcc
	s_add_i32 m0, s62, 0x2000
	s_waitcnt vmcnt(5)
	global_load_lds_dwordx4 v208, vcc
	s_barrier
	v_mfma_f32_16x16x32_bf16 v[54:57], v[178:181], v[146:149], v[54:57]
	v_mfma_f32_16x16x32_bf16 v[50:53], v[186:189], v[146:149], v[50:53]
	v_mfma_f32_16x16x32_bf16 v[38:41], v[178:181], v[154:157], v[38:41]
	v_mfma_f32_16x16x32_bf16 v[34:37], v[186:189], v[154:157], v[34:37]
	v_mfma_f32_16x16x32_bf16 v[22:25], v[178:181], v[162:165], v[22:25]
	v_mfma_f32_16x16x32_bf16 v[18:21], v[186:189], v[162:165], v[18:21]
	v_mfma_f32_16x16x32_bf16 v[6:9], v[178:181], v[170:173], v[6:9]
	v_mfma_f32_16x16x32_bf16 v[2:5], v[186:189], v[170:173], v[2:5]
	v_mfma_f32_16x16x32_bf16 v[54:57], v[182:185], v[150:153], v[54:57]
	v_mfma_f32_16x16x32_bf16 v[50:53], v[190:193], v[150:153], v[50:53]
	v_mfma_f32_16x16x32_bf16 v[38:41], v[182:185], v[158:161], v[38:41]
	v_mfma_f32_16x16x32_bf16 v[34:37], v[190:193], v[158:161], v[34:37]
	v_mfma_f32_16x16x32_bf16 v[22:25], v[182:185], v[166:169], v[22:25]
	v_mfma_f32_16x16x32_bf16 v[18:21], v[190:193], v[166:169], v[18:21]
	v_mfma_f32_16x16x32_bf16 v[6:9], v[182:185], v[174:177], v[6:9]
	v_mfma_f32_16x16x32_bf16 v[2:5], v[190:193], v[174:177], v[2:5]
	s_cmp_ge_u32 s84, s74
	s_mov_b32 s62, s84
	s_barrier
	s_cbranch_scc0 .LBB0_654
	s_waitcnt lgkmcnt(0)
	v_lshl_or_b32 v218, s81, 8, v242
	v_ashrrev_i32_e32 v219, 31, v218
	v_lshl_add_u32 v220, s80, 8, v240
	v_lshlrev_b64 v[146:147], 2, v[218:219]
	v_ashrrev_i32_e32 v221, 31, v220
	v_lshl_add_u64 v[62:63], s[44:45], 0, v[146:147]
	v_lshl_add_u64 v[222:223], s[54:55], 0, v[146:147]
	v_lshlrev_b64 v[146:147], 13, v[220:221]
	v_lshl_add_u64 v[146:147], v[222:223], 0, v[146:147]
	global_load_dwordx4 v[66:69], v[62:63], off offset:16
	global_load_dwordx4 v[70:73], v[62:63], off
	global_load_dwordx4 v[58:61], v[62:63], off offset:528
	s_nop 0
	global_load_dwordx4 v[62:65], v[62:63], off offset:512
	s_nop 0
	global_load_dwordx4 v[246:249], v[146:147], off offset:16 nt
	global_load_dwordx4 v[202:205], v[146:147], off nt
	global_load_dwordx4 v[194:197], v[146:147], off offset:528 nt
	global_load_dwordx4 v[198:201], v[146:147], off offset:512 nt
	v_or_b32_e32 v228, 16, v220
	v_and_b32_e32 v149, 64, v234
	v_ashrrev_i32_e32 v229, 31, v228
	v_xor_b32_e32 v148, 16, v234
	v_add_u32_e32 v149, 64, v149
	v_lshlrev_b64 v[146:147], 13, v[228:229]
	v_or_b32_e32 v226, 32, v220
	v_cmp_lt_i32_e32 vcc, v148, v149
	v_lshl_add_u64 v[146:147], v[222:223], 0, v[146:147]
	v_ashrrev_i32_e32 v227, 31, v226
	v_cndmask_b32_e32 v148, v234, v148, vcc
	global_load_dwordx4 v[186:189], v[146:147], off offset:16 nt
	global_load_dwordx4 v[190:193], v[146:147], off nt
	global_load_dwordx4 v[178:181], v[146:147], off offset:528 nt
	global_load_dwordx4 v[182:185], v[146:147], off offset:512 nt
	v_lshlrev_b64 v[146:147], 13, v[226:227]
	v_or_b32_e32 v224, 48, v220
	v_lshlrev_b32_e32 v245, 2, v148
	v_xor_b32_e32 v148, 32, v234
	v_lshl_add_u64 v[146:147], v[222:223], 0, v[146:147]
	v_ashrrev_i32_e32 v225, 31, v224
	v_cmp_lt_i32_e32 vcc, v148, v149
	global_load_dwordx4 v[170:173], v[146:147], off offset:16 nt
	global_load_dwordx4 v[174:177], v[146:147], off nt
	global_load_dwordx4 v[154:157], v[146:147], off offset:528 nt
	global_load_dwordx4 v[158:161], v[146:147], off offset:512 nt
	v_lshlrev_b64 v[146:147], 13, v[224:225]
	v_cndmask_b32_e32 v148, v234, v148, vcc
	v_lshl_add_u64 v[150:151], v[222:223], 0, v[146:147]
	v_lshlrev_b32_e32 v244, 2, v148
	global_load_dwordx4 v[162:165], v[150:151], off offset:16 nt
	global_load_dwordx4 v[166:169], v[150:151], off nt
	global_load_dwordx4 v[146:149], v[150:151], off offset:528 nt
	s_nop 0
	global_load_dwordx4 v[150:153], v[150:151], off offset:512 nt
	v_lshlrev_b64 v[230:231], 11, v[220:221]
	v_readlane_b32 s60, v251, 56
	v_lshl_add_u64 v[230:231], v[230:231], 0, v[218:219]
	v_readlane_b32 s61, v251, 57
	v_readlane_b32 s62, v254, 8
	v_readlane_b32 s63, v254, 9
	s_waitcnt vmcnt(0)
	v_pk_fma_f32 v[140:141], s[58:59], v[140:141], v[248:249]
	v_pk_fma_f32 v[144:145], s[58:59], v[144:145], v[204:205]
	v_pk_fma_f32 v[142:143], s[46:47], v[142:143], v[202:203]
	v_lshl_add_u64 v[202:203], v[230:231], 2, s[60:61]
	v_pk_fma_f32 v[138:139], s[46:47], v[138:139], v[246:247]
	global_store_dwordx4 v[202:203], v[142:145], off nt
	global_store_dwordx4 v[202:203], v[138:141], off offset:16 nt
	v_mul_f32_e32 v202, v143, v143
	v_mul_f32_e32 v203, v145, v145
	v_fmac_f32_e32 v202, v142, v142
	v_fmac_f32_e32 v203, v144, v144
	v_add_f32_e32 v202, v202, v203
	v_mul_f32_e32 v203, v139, v139
	v_fmac_f32_e32 v203, v138, v138
	v_add_f32_e32 v202, v203, v202
	v_mul_f32_e32 v203, v141, v141
	v_fmac_f32_e32 v203, v140, v140
	v_add_f32_e32 v204, v203, v202
	v_pk_mul_f32 v[144:145], v[72:73], v[144:145]
	v_pk_mul_f32 v[142:143], v[70:71], v[142:143]
	v_pk_mul_f32 v[202:203], v[68:69], v[140:141]
	v_pk_mul_f32 v[140:141], v[66:67], v[138:139]
	v_cvt_pk_bf16_f32 v138, v142, v143
	v_cvt_pk_bf16_f32 v139, v144, v145
	v_cvt_pk_bf16_f32 v140, v140, v141
	v_cvt_pk_bf16_f32 v141, v202, v203
	v_lshl_add_u64 v[142:143], v[230:231], 1, s[62:63]
	v_or_b32_e32 v230, 0x80, v230
	global_store_dwordx4 v[142:143], v[138:141], off
	v_pk_fma_f32 v[136:137], s[58:59], v[136:137], v[200:201]
	v_pk_fma_f32 v[134:135], s[46:47], v[134:135], v[198:199]
	v_lshl_add_u64 v[138:139], v[230:231], 2, s[60:61]
	v_pk_fma_f32 v[132:133], s[58:59], v[132:133], v[196:197]
	v_pk_fma_f32 v[130:131], s[46:47], v[130:131], v[194:195]
	global_store_dwordx4 v[138:139], v[134:137], off nt
	global_store_dwordx4 v[138:139], v[130:133], off offset:16 nt
	v_mul_f32_e32 v138, v135, v135
	v_mul_f32_e32 v139, v137, v137
	v_fmac_f32_e32 v138, v134, v134
	v_fmac_f32_e32 v139, v136, v136
	v_add_f32_e32 v138, v138, v139
	v_mul_f32_e32 v139, v131, v131
	v_fmac_f32_e32 v139, v130, v130
	v_add_f32_e32 v138, v139, v138
	v_mul_f32_e32 v139, v133, v133
	v_fmac_f32_e32 v139, v132, v132
	v_add_f32_e32 v138, v139, v138
	v_add_f32_e32 v140, v204, v138
	v_pk_mul_f32 v[136:137], v[64:65], v[136:137]
	v_pk_mul_f32 v[134:135], v[62:63], v[134:135]
	v_pk_mul_f32 v[138:139], v[60:61], v[132:133]
	v_pk_mul_f32 v[132:133], v[58:59], v[130:131]
	v_cvt_pk_bf16_f32 v130, v134, v135
	v_cvt_pk_bf16_f32 v131, v136, v137
	v_cvt_pk_bf16_f32 v132, v132, v133
	v_cvt_pk_bf16_f32 v133, v138, v139
	v_lshl_add_u64 v[134:135], v[230:231], 1, s[62:63]
	global_store_dwordx4 v[134:135], v[130:133], off
	ds_bpermute_b32 v130, v245, v140
	v_lshl_add_u64 v[138:139], v[220:221], 2, s[56:57]
	s_waitcnt lgkmcnt(0)
	v_add_f32_e32 v130, v140, v130
	ds_bpermute_b32 v131, v244, v130
	s_and_saveexec_b64 s[60:61], s[36:37]
	s_cbranch_execz .LBB0_657
	s_waitcnt lgkmcnt(0)
	v_add_f32_e32 v130, v130, v131
	global_atomic_add_f32 v[138:139], v130, off
